# baseline (speedup 1.0000x reference)
; #define G_STAGE(bufoff, gbase, voff) do { _Pragma("unroll") for (int _i = 0; _i < 2; ++_i) \
;         __builtin_amdgcn_global_load_lds((const unsigned*)((const char*)(gbase) + (voff)[_i]), (LAS unsigned*)(lds + (bufoff) + ldsw + _i * 8192), 16, 0, 0); } while (0)
; #define G_LDA(dst, b, h) do { _Pragma("unroll") for (int m = 0; m < 4; ++m) _Pragma("unroll") for (int k = 0; k < 2; ++k) dst[m][k] = *(const LAS bf16x8*)(lds + G_SA(b, h) + aoff + m * 2048 + k * 1024); } while (0)
; #define G_LDB(dst, b, h) do { _Pragma("unroll") for (int n = 0; n < 2; ++n) _Pragma("unroll") for (int k = 0; k < 2; ++k) dst[n][k] = *(const LAS bf16x8*)(lds + G_SB(b, h) + boff + n * 2048 + k * 1024); } while (0)
; #define G_MMA(ai, bj, At, Bt) do { __builtin_amdgcn_s_setprio(1); _Pragma("unroll") for (int m = 0; m < 4; ++m) _Pragma("unroll") for (int n = 0; n < 2; ++n) _Pragma("unroll") for (int k = 0; k < 2; ++k) \
;         acc[ai][bj][m][n] = __builtin_amdgcn_mfma_f32_16x16x32_bf16(Bt[n][k], At[m][k], acc[ai][bj][m][n], 0, 0, 0); __builtin_amdgcn_s_setprio(0); } while (0)
; #define G_WAIT_V(n) asm volatile("s_waitcnt vmcnt(" #n ")" ::: "memory")
; #define G_WAIT_L(n) asm volatile("s_waitcnt lgkmcnt(" #n ")" ::: "memory")
; #define G_BAR __builtin_amdgcn_s_barrier()
; #define G_SCHED __builtin_amdgcn_sched_barrier(0)
; template <class J>
; DI void gemm_phase(LAS unsigned char* lds, const J& job) {
;     ...
;       const bool last = (t == nt - 2);
;       const char* a1 = cA + G_KT(t + 1);
;       const char* a2 = last ? nA + G_KT(0) : cA + G_KT(t + 2); const char* b2 = last ? nB + G_KT(0) : cB + G_KT(t + 2);
;       const char* a3 = last ? nA + G_KT(1) : cA + G_KT(t + 3); const char* b3 = last ? nB + G_KT(1) : cB + G_KT(t + 3);
;       G_LDB(B0, 0, 0); G_SCHED; G_LDA(At, 0, 0); G_STAGE(G_SA(1, 1), a1 + hstepA, voffA);
;       G_WAIT_L(8); G_BAR; G_WAIT_L(0); G_MMA(0, 0, At, B0); G_BAR; G_SCHED;
;       G_LDB(B1, 0, 1); G_STAGE(G_SB(0, 0), b2, voffB);
;       G_BAR; G_WAIT_L(0); G_MMA(0, 1, At, B1); G_BAR;
;       G_LDA(At, 0, 1); G_STAGE(G_SA(0, 0), a2, voffA);
;       G_BAR; G_WAIT_L(0); G_MMA(1, 0, At, B0); G_BAR; G_SCHED;
;       G_STAGE(G_SB(0, 1), b2 + hstepB, voffB);
;       G_WAIT_V(6); G_BAR; G_MMA(1, 1, At, B1); G_BAR;
.LBB0_42:
	s_add_i32 s1, s57, 0xffffff80
	s_and_b32 s0, s44, 0xf80
	s_and_b32 s1, s1, 0xf00
	s_add_u32 s2, s70, s1
	s_addc_u32 s72, s71, 0
	s_add_u32 s1, s68, s1
	s_addc_u32 s73, s69, 0
	s_and_b32 s74, s57, 0xf80
	s_add_u32 s80, s70, s74
	s_addc_u32 s75, s71, 0
	s_add_u32 s54, s68, s74
	s_addc_u32 s55, s69, 0
	s_cmp_eq_u32 s7, 28
	s_cselect_b32 s77, vcc_lo, s72
	s_cselect_b32 s76, s47, s2
	s_cselect_b32 s79, s33, s73
	s_cselect_b32 s78, vcc_hi, s1
	s_cselect_b32 s75, s4, s75
	s_cselect_b32 s74, s97, s80
	s_cselect_b32 s73, s6, s55
	s_cselect_b32 s72, s5, s54
	s_add_i32 s2, s84, 0x100
	v_add_u32_e32 v140, s2, v162
	ds_read_b128 v[128:131], v140
	ds_read_b128 v[132:135], v140 offset:1024
	ds_read_b128 v[136:139], v140 offset:2048
	ds_read_b128 v[140:143], v140 offset:3072
	s_add_u32 s0, s21, s0
	s_addc_u32 s1, s23, 0
	v_lshl_add_u64 v[158:159], s[0:1], 0, v[148:149]
	s_add_i32 m0, s25, 0xc000
	ds_read_b128 v[154:157], v163
	ds_read_b128 v[164:167], v163 offset:1024
	ds_read_b128 v[168:171], v163 offset:2048
	ds_read_b128 v[172:175], v163 offset:3072
	ds_read_b128 v[176:179], v163 offset:4096
	ds_read_b128 v[180:183], v163 offset:5120
	ds_read_b128 v[184:187], v163 offset:6144
	ds_read_b128 v[188:191], v163 offset:7168
	global_load_lds_dwordx4 v[158:159], off
	v_lshl_add_u64 v[158:159], s[0:1], 0, v[150:151]
	s_add_i32 m0, s25, 0xe000
	s_nop 0
	global_load_lds_dwordx4 v[158:159], off
	s_waitcnt lgkmcnt(8)
	s_barrier
	s_waitcnt lgkmcnt(0)
	v_mfma_f32_16x16x32_bf16 v[124:127], v[128:131], v[154:157], v[124:127]
	v_mfma_f32_16x16x32_bf16 v[120:123], v[136:139], v[154:157], v[120:123]
	v_mfma_f32_16x16x32_bf16 v[108:111], v[128:131], v[168:171], v[108:111]
	v_mfma_f32_16x16x32_bf16 v[104:107], v[136:139], v[168:171], v[104:107]
	v_mfma_f32_16x16x32_bf16 v[92:95], v[128:131], v[176:179], v[92:95]
	v_mfma_f32_16x16x32_bf16 v[88:91], v[136:139], v[176:179], v[88:91]
	v_mfma_f32_16x16x32_bf16 v[76:79], v[128:131], v[184:187], v[76:79]
	v_mfma_f32_16x16x32_bf16 v[72:75], v[136:139], v[184:187], v[72:75]
	v_mfma_f32_16x16x32_bf16 v[124:127], v[132:135], v[164:167], v[124:127]
	v_mfma_f32_16x16x32_bf16 v[120:123], v[140:143], v[164:167], v[120:123]
	v_mfma_f32_16x16x32_bf16 v[108:111], v[132:135], v[172:175], v[108:111]
	v_mfma_f32_16x16x32_bf16 v[104:107], v[140:143], v[172:175], v[104:107]
	v_mfma_f32_16x16x32_bf16 v[92:95], v[132:135], v[180:183], v[92:95]
	v_mfma_f32_16x16x32_bf16 v[88:91], v[140:143], v[180:183], v[88:91]
	v_mfma_f32_16x16x32_bf16 v[76:79], v[132:135], v[188:191], v[76:79]
	v_mfma_f32_16x16x32_bf16 v[72:75], v[140:143], v[188:191], v[72:75]
	s_barrier
	s_add_i32 s54, s85, 0x100
	v_add_u32_e32 v158, s54, v162
	s_add_i32 s0, s2, s14
	ds_read_b128 v[192:195], v158
	ds_read_b128 v[196:199], v158 offset:1024
	ds_read_b128 v[200:203], v158 offset:2048
	ds_read_b128 v[204:207], v158 offset:3072
	v_lshl_add_u64 v[158:159], s[78:79], 0, v[146:147]
	s_mov_b32 m0, s0
	s_nop 0
	global_load_lds_dwordx4 v[158:159], off
	v_lshl_add_u64 v[158:159], s[78:79], 0, v[152:153]
	s_add_i32 m0, s0, 0x2000
	s_nop 0
	global_load_lds_dwordx4 v[158:159], off
	s_barrier
	s_waitcnt lgkmcnt(0)
	v_mfma_f32_16x16x32_bf16 v[116:119], v[192:195], v[154:157], v[116:119]
	v_mfma_f32_16x16x32_bf16 v[112:115], v[200:203], v[154:157], v[112:115]
	v_mfma_f32_16x16x32_bf16 v[100:103], v[192:195], v[168:171], v[100:103]
	v_mfma_f32_16x16x32_bf16 v[96:99], v[200:203], v[168:171], v[96:99]
	v_mfma_f32_16x16x32_bf16 v[84:87], v[192:195], v[176:179], v[84:87]
	v_mfma_f32_16x16x32_bf16 v[80:83], v[200:203], v[176:179], v[80:83]
	v_mfma_f32_16x16x32_bf16 v[68:71], v[192:195], v[184:187], v[68:71]
	v_mfma_f32_16x16x32_bf16 v[64:67], v[200:203], v[184:187], v[64:67]
	v_mfma_f32_16x16x32_bf16 v[116:119], v[196:199], v[164:167], v[116:119]
	v_mfma_f32_16x16x32_bf16 v[112:115], v[204:207], v[164:167], v[112:115]
	v_mfma_f32_16x16x32_bf16 v[100:103], v[196:199], v[172:175], v[100:103]
	v_mfma_f32_16x16x32_bf16 v[96:99], v[204:207], v[172:175], v[96:99]
	v_mfma_f32_16x16x32_bf16 v[84:87], v[196:199], v[180:183], v[84:87]
	v_mfma_f32_16x16x32_bf16 v[80:83], v[204:207], v[180:183], v[80:83]
	v_mfma_f32_16x16x32_bf16 v[68:71], v[196:199], v[188:191], v[68:71]
	v_mfma_f32_16x16x32_bf16 v[64:67], v[204:207], v[188:191], v[64:67]
	s_barrier
	s_mov_b32 m0, s25
	v_lshl_add_u64 v[158:159], s[76:77], 0, v[148:149]
	ds_read_b128 v[154:157], v163 offset:16384
	ds_read_b128 v[164:167], v163 offset:17408
	ds_read_b128 v[168:171], v163 offset:18432
	ds_read_b128 v[172:175], v163 offset:19456
	ds_read_b128 v[176:179], v163 offset:20480
	ds_read_b128 v[180:183], v163 offset:21504
	ds_read_b128 v[184:187], v163 offset:22528
	ds_read_b128 v[188:191], v163 offset:23552
	global_load_lds_dwordx4 v[158:159], off
	v_lshl_add_u64 v[158:159], s[76:77], 0, v[150:151]
	s_mov_b32 m0, s36
	s_nop 0
	global_load_lds_dwordx4 v[158:159], off
	s_barrier
	s_waitcnt lgkmcnt(0)
	v_mfma_f32_16x16x32_bf16 v[60:63], v[128:131], v[154:157], v[60:63]
	v_mfma_f32_16x16x32_bf16 v[56:59], v[136:139], v[154:157], v[56:59]
	v_mfma_f32_16x16x32_bf16 v[44:47], v[128:131], v[168:171], v[44:47]
	v_mfma_f32_16x16x32_bf16 v[40:43], v[136:139], v[168:171], v[40:43]
	v_mfma_f32_16x16x32_bf16 v[28:31], v[128:131], v[176:179], v[28:31]
	v_mfma_f32_16x16x32_bf16 v[24:27], v[136:139], v[176:179], v[24:27]
	v_mfma_f32_16x16x32_bf16 v[20:23], v[128:131], v[184:187], v[20:23]
	v_mfma_f32_16x16x32_bf16 v[12:15], v[136:139], v[184:187], v[12:15]
	v_mfma_f32_16x16x32_bf16 v[60:63], v[132:135], v[164:167], v[60:63]
	v_mfma_f32_16x16x32_bf16 v[56:59], v[140:143], v[164:167], v[56:59]
	v_mfma_f32_16x16x32_bf16 v[44:47], v[132:135], v[172:175], v[44:47]
	v_mfma_f32_16x16x32_bf16 v[40:43], v[140:143], v[172:175], v[40:43]
	v_mfma_f32_16x16x32_bf16 v[28:31], v[132:135], v[180:183], v[28:31]
	v_mfma_f32_16x16x32_bf16 v[24:27], v[140:143], v[180:183], v[24:27]
	v_mfma_f32_16x16x32_bf16 v[20:23], v[132:135], v[188:191], v[20:23]
	v_mfma_f32_16x16x32_bf16 v[12:15], v[140:143], v[188:191], v[12:15]
	s_barrier
; #define G_STAGE(bufoff, gbase, voff) do { _Pragma("unroll") for (int _i = 0; _i < 2; ++_i) \
;         __builtin_amdgcn_global_load_lds((const unsigned*)((const char*)(gbase) + (voff)[_i]), (LAS unsigned*)(lds + (bufoff) + ldsw + _i * 8192), 16, 0, 0); } while (0)
; #define G_LDA(dst, b, h) do { _Pragma("unroll") for (int m = 0; m < 4; ++m) _Pragma("unroll") for (int k = 0; k < 2; ++k) dst[m][k] = *(const LAS bf16x8*)(lds + G_SA(b, h) + aoff + m * 2048 + k * 1024); } while (0)
; #define G_LDB(dst, b, h) do { _Pragma("unroll") for (int n = 0; n < 2; ++n) _Pragma("unroll") for (int k = 0; k < 2; ++k) dst[n][k] = *(const LAS bf16x8*)(lds + G_SB(b, h) + boff + n * 2048 + k * 1024); } while (0)
; #define G_MMA(ai, bj, At, Bt) do { __builtin_amdgcn_s_setprio(1); _Pragma("unroll") for (int m = 0; m < 4; ++m) _Pragma("unroll") for (int n = 0; n < 2; ++n) _Pragma("unroll") for (int k = 0; k < 2; ++k) \
;         acc[ai][bj][m][n] = __builtin_amdgcn_mfma_f32_16x16x32_bf16(Bt[n][k], At[m][k], acc[ai][bj][m][n], 0, 0, 0); __builtin_amdgcn_s_setprio(0); } while (0)
; #define G_WAIT_V(n) asm volatile("s_waitcnt vmcnt(" #n ")" ::: "memory")
; #define G_WAIT_L(n) asm volatile("s_waitcnt lgkmcnt(" #n ")" ::: "memory")
; #define G_BAR __builtin_amdgcn_s_barrier()
; #define G_SCHED __builtin_amdgcn_sched_barrier(0)
; template <class J>
; DI void gemm_phase(LAS unsigned char* lds, const J& job) {
;     ...
;       G_STAGE(G_SB(0, 1), b2 + hstepB, voffB);
;       G_WAIT_V(6); G_BAR; G_MMA(1, 1, At, B1); G_BAR;
;       G_LDB(B0, 1, 0); G_SCHED; G_LDA(At, 1, 0); G_STAGE(G_SA(0, 1), a2 + hstepA, voffA);
;       G_WAIT_L(8); G_BAR; G_WAIT_L(0); G_MMA(0, 0, At, B0); G_BAR; G_SCHED;
;       G_LDB(B1, 1, 1); G_STAGE(G_SB(1, 0), b3, voffB);
;       G_BAR; G_WAIT_L(0); G_MMA(0, 1, At, B1); G_BAR;
;       G_LDA(At, 1, 1); G_STAGE(G_SA(1, 0), a3, voffA);
;       G_BAR; G_WAIT_L(0); G_MMA(1, 0, At, B0); G_BAR; G_SCHED;
	s_add_u32 s0, s78, 0x80000
	s_addc_u32 s1, s79, 0
	s_add_i32 s2, s54, s14
	v_lshl_add_u64 v[128:129], s[0:1], 0, v[146:147]
	s_mov_b32 m0, s2
	s_nop 0
	global_load_lds_dwordx4 v[128:129], off
	v_lshl_add_u64 v[128:129], s[0:1], 0, v[152:153]
	s_add_i32 m0, s2, 0x2000
	s_nop 0
	global_load_lds_dwordx4 v[128:129], off
	s_waitcnt vmcnt(6)
	s_barrier
	v_mfma_f32_16x16x32_bf16 v[52:55], v[192:195], v[154:157], v[52:55]
	v_mfma_f32_16x16x32_bf16 v[48:51], v[200:203], v[154:157], v[48:51]
	v_mfma_f32_16x16x32_bf16 v[36:39], v[192:195], v[168:171], v[36:39]
	v_mfma_f32_16x16x32_bf16 v[32:35], v[200:203], v[168:171], v[32:35]
	v_mfma_f32_16x16x32_bf16 v[16:19], v[192:195], v[176:179], v[16:19]
	v_mfma_f32_16x16x32_bf16 v[8:11], v[200:203], v[176:179], v[8:11]
	v_mfma_f32_16x16x32_bf16 v[4:7], v[192:195], v[184:187], v[4:7]
	v_mfma_f32_16x16x32_bf16 v[0:3], v[200:203], v[184:187], v[0:3]
	v_mfma_f32_16x16x32_bf16 v[52:55], v[196:199], v[164:167], v[52:55]
	v_mfma_f32_16x16x32_bf16 v[48:51], v[204:207], v[164:167], v[48:51]
	v_mfma_f32_16x16x32_bf16 v[36:39], v[196:199], v[172:175], v[36:39]
	v_mfma_f32_16x16x32_bf16 v[32:35], v[204:207], v[172:175], v[32:35]
	v_mfma_f32_16x16x32_bf16 v[16:19], v[196:199], v[180:183], v[16:19]
	v_mfma_f32_16x16x32_bf16 v[8:11], v[204:207], v[180:183], v[8:11]
	v_mfma_f32_16x16x32_bf16 v[4:7], v[196:199], v[188:191], v[4:7]
	v_mfma_f32_16x16x32_bf16 v[0:3], v[204:207], v[188:191], v[0:3]
	s_barrier
	s_add_i32 s2, s88, 0x100
	v_add_u32_e32 v140, s2, v162
	ds_read_b128 v[128:131], v140
	ds_read_b128 v[132:135], v140 offset:1024
	ds_read_b128 v[136:139], v140 offset:2048
	ds_read_b128 v[140:143], v140 offset:3072
	s_add_u32 s0, s76, 0x80000
	s_addc_u32 s1, s77, 0
	s_mov_b32 m0, s37
	v_lshl_add_u64 v[158:159], s[0:1], 0, v[148:149]
	ds_read_b128 v[154:157], v163 offset:32768
	ds_read_b128 v[164:167], v163 offset:33792
	ds_read_b128 v[168:171], v163 offset:34816
	ds_read_b128 v[172:175], v163 offset:35840
	ds_read_b128 v[176:179], v163 offset:36864
	ds_read_b128 v[180:183], v163 offset:37888
	ds_read_b128 v[184:187], v163 offset:38912
	ds_read_b128 v[188:191], v163 offset:39936
	global_load_lds_dwordx4 v[158:159], off
	v_lshl_add_u64 v[158:159], s[0:1], 0, v[150:151]
	s_mov_b32 m0, s38
	s_nop 0
	global_load_lds_dwordx4 v[158:159], off
	s_waitcnt lgkmcnt(8)
	s_barrier
	s_waitcnt lgkmcnt(0)
	v_mfma_f32_16x16x32_bf16 v[124:127], v[128:131], v[154:157], v[124:127]
	v_mfma_f32_16x16x32_bf16 v[120:123], v[136:139], v[154:157], v[120:123]
	v_mfma_f32_16x16x32_bf16 v[108:111], v[128:131], v[168:171], v[108:111]
	v_mfma_f32_16x16x32_bf16 v[104:107], v[136:139], v[168:171], v[104:107]
	v_mfma_f32_16x16x32_bf16 v[92:95], v[128:131], v[176:179], v[92:95]
	v_mfma_f32_16x16x32_bf16 v[88:91], v[136:139], v[176:179], v[88:91]
	v_mfma_f32_16x16x32_bf16 v[76:79], v[128:131], v[184:187], v[76:79]
	v_mfma_f32_16x16x32_bf16 v[72:75], v[136:139], v[184:187], v[72:75]
	v_mfma_f32_16x16x32_bf16 v[124:127], v[132:135], v[164:167], v[124:127]
	v_mfma_f32_16x16x32_bf16 v[120:123], v[140:143], v[164:167], v[120:123]
	v_mfma_f32_16x16x32_bf16 v[108:111], v[132:135], v[172:175], v[108:111]
	v_mfma_f32_16x16x32_bf16 v[104:107], v[140:143], v[172:175], v[104:107]
	v_mfma_f32_16x16x32_bf16 v[92:95], v[132:135], v[180:183], v[92:95]
	v_mfma_f32_16x16x32_bf16 v[88:91], v[140:143], v[180:183], v[88:91]
	v_mfma_f32_16x16x32_bf16 v[76:79], v[132:135], v[188:191], v[76:79]
	v_mfma_f32_16x16x32_bf16 v[72:75], v[140:143], v[188:191], v[72:75]
	s_barrier
	s_add_i32 s54, s89, 0x100
	v_add_u32_e32 v158, s54, v162
	s_add_i32 s0, s2, s14
	ds_read_b128 v[192:195], v158
	ds_read_b128 v[196:199], v158 offset:1024
	ds_read_b128 v[200:203], v158 offset:2048
	ds_read_b128 v[204:207], v158 offset:3072
	v_lshl_add_u64 v[158:159], s[72:73], 0, v[146:147]
	s_mov_b32 m0, s0
	s_nop 0
	global_load_lds_dwordx4 v[158:159], off
	v_lshl_add_u64 v[158:159], s[72:73], 0, v[152:153]
	s_add_i32 m0, s0, 0x2000
	s_nop 0
	global_load_lds_dwordx4 v[158:159], off
	s_barrier
	s_waitcnt lgkmcnt(0)
	v_mfma_f32_16x16x32_bf16 v[116:119], v[192:195], v[154:157], v[116:119]
	v_mfma_f32_16x16x32_bf16 v[112:115], v[200:203], v[154:157], v[112:115]
	v_mfma_f32_16x16x32_bf16 v[100:103], v[192:195], v[168:171], v[100:103]
	v_mfma_f32_16x16x32_bf16 v[96:99], v[200:203], v[168:171], v[96:99]
	v_mfma_f32_16x16x32_bf16 v[84:87], v[192:195], v[176:179], v[84:87]
	v_mfma_f32_16x16x32_bf16 v[80:83], v[200:203], v[176:179], v[80:83]
	v_mfma_f32_16x16x32_bf16 v[68:71], v[192:195], v[184:187], v[68:71]
	v_mfma_f32_16x16x32_bf16 v[64:67], v[200:203], v[184:187], v[64:67]
	v_mfma_f32_16x16x32_bf16 v[116:119], v[196:199], v[164:167], v[116:119]
	v_mfma_f32_16x16x32_bf16 v[112:115], v[204:207], v[164:167], v[112:115]
	v_mfma_f32_16x16x32_bf16 v[100:103], v[196:199], v[172:175], v[100:103]
	v_mfma_f32_16x16x32_bf16 v[96:99], v[204:207], v[172:175], v[96:99]
	v_mfma_f32_16x16x32_bf16 v[84:87], v[196:199], v[180:183], v[84:87]
	v_mfma_f32_16x16x32_bf16 v[80:83], v[204:207], v[180:183], v[80:83]
	v_mfma_f32_16x16x32_bf16 v[68:71], v[196:199], v[188:191], v[68:71]
	v_mfma_f32_16x16x32_bf16 v[64:67], v[204:207], v[188:191], v[64:67]
	s_barrier
; #define G_STAGE(bufoff, gbase, voff) do { _Pragma("unroll") for (int _i = 0; _i < 2; ++_i) \
;         __builtin_amdgcn_global_load_lds((const unsigned*)((const char*)(gbase) + (voff)[_i]), (LAS unsigned*)(lds + (bufoff) + ldsw + _i * 8192), 16, 0, 0); } while (0)
; #define G_MMA(ai, bj, At, Bt) do { __builtin_amdgcn_s_setprio(1); _Pragma("unroll") for (int m = 0; m < 4; ++m) _Pragma("unroll") for (int n = 0; n < 2; ++n) _Pragma("unroll") for (int k = 0; k < 2; ++k) \
;         acc[ai][bj][m][n] = __builtin_amdgcn_mfma_f32_16x16x32_bf16(Bt[n][k], At[m][k], acc[ai][bj][m][n], 0, 0, 0); __builtin_amdgcn_s_setprio(0); } while (0)
; #define G_WAIT_V(n) asm volatile("s_waitcnt vmcnt(" #n ")" ::: "memory")
; #define G_WAIT_L(n) asm volatile("s_waitcnt lgkmcnt(" #n ")" ::: "memory")
; #define G_BAR __builtin_amdgcn_s_barrier()
; #define G_SCHED __builtin_amdgcn_sched_barrier(0)
; template <class J>
; DI void gemm_phase(LAS unsigned char* lds, const J& job) {
;     ...
;       G_BAR; G_WAIT_L(0); G_MMA(1, 0, At, B0); G_BAR; G_SCHED;
;       G_STAGE(G_SB(1, 1), b3 + hstepB, voffB);
;       G_WAIT_V(6); G_BAR; G_MMA(1, 1, At, B1); G_BAR;
;   DI void epi(const Acc& acc, const Unit& u, int wr, int wc, int fr, int fq) const {
;     ...
;     for (int ai = 0; ai < 2; ++ai) {
;       f32x4 res[4][2][2];
; #pragma unroll
;       for (int m = 0; m < 4; ++m) {
;         const int row = u.pm * 256 + ai * HALF + wr * 64 + m * 16 + fr;
;         const float* src = (l == 0) ? xp + (size_t)row * DM : out + (size_t)row * DM;
; #pragma unroll
;         for (int bj = 0; bj < 2; ++bj) { const int col = u.pn * 256 + bj * HALF + wc * 32 + 8 * fq; res[m][bj][0] = *(const f32x4*)(src + col); res[m][bj][1] = *(const f32x4*)(src + col + 4); }
;       }
	s_mov_b32 m0, s87
	v_lshl_add_u64 v[158:159], s[74:75], 0, v[148:149]
	ds_read_b128 v[154:157], v163 offset:49152
	ds_read_b128 v[164:167], v163 offset:50176
	ds_read_b128 v[168:171], v163 offset:51200
	ds_read_b128 v[172:175], v163 offset:52224
	ds_read_b128 v[176:179], v163 offset:53248
	ds_read_b128 v[180:183], v163 offset:54272
	ds_read_b128 v[184:187], v163 offset:55296
	ds_read_b128 v[188:191], v163 offset:56320
	global_load_lds_dwordx4 v[158:159], off
	v_lshl_add_u64 v[158:159], s[74:75], 0, v[150:151]
	s_mov_b32 m0, s94
	s_nop 0
	global_load_lds_dwordx4 v[158:159], off
	s_barrier
	s_waitcnt lgkmcnt(0)
	v_mfma_f32_16x16x32_bf16 v[60:63], v[128:131], v[154:157], v[60:63]
	v_mfma_f32_16x16x32_bf16 v[56:59], v[136:139], v[154:157], v[56:59]
	v_mfma_f32_16x16x32_bf16 v[44:47], v[128:131], v[168:171], v[44:47]
	v_mfma_f32_16x16x32_bf16 v[40:43], v[136:139], v[168:171], v[40:43]
	v_mfma_f32_16x16x32_bf16 v[28:31], v[128:131], v[176:179], v[28:31]
	v_mfma_f32_16x16x32_bf16 v[24:27], v[136:139], v[176:179], v[24:27]
	v_mfma_f32_16x16x32_bf16 v[20:23], v[128:131], v[184:187], v[20:23]
	v_mfma_f32_16x16x32_bf16 v[12:15], v[136:139], v[184:187], v[12:15]
	v_mfma_f32_16x16x32_bf16 v[60:63], v[132:135], v[164:167], v[60:63]
	v_mfma_f32_16x16x32_bf16 v[56:59], v[140:143], v[164:167], v[56:59]
	v_mfma_f32_16x16x32_bf16 v[44:47], v[132:135], v[172:175], v[44:47]
	v_mfma_f32_16x16x32_bf16 v[40:43], v[140:143], v[172:175], v[40:43]
	v_mfma_f32_16x16x32_bf16 v[28:31], v[132:135], v[180:183], v[28:31]
	v_mfma_f32_16x16x32_bf16 v[24:27], v[140:143], v[180:183], v[24:27]
	v_mfma_f32_16x16x32_bf16 v[20:23], v[132:135], v[188:191], v[20:23]
	v_mfma_f32_16x16x32_bf16 v[12:15], v[140:143], v[188:191], v[12:15]
	s_barrier
	s_add_u32 s0, s72, 0x80000
	s_addc_u32 s1, s73, 0
	s_add_i32 s2, s54, s14
	v_lshl_add_u64 v[128:129], s[0:1], 0, v[146:147]
	s_mov_b32 m0, s2
	s_nop 0
	global_load_lds_dwordx4 v[128:129], off
	v_lshl_add_u64 v[128:129], s[0:1], 0, v[152:153]
	s_add_i32 m0, s2, 0x2000
	s_nop 0
	global_load_lds_dwordx4 v[128:129], off
	s_waitcnt vmcnt(6)
	s_barrier
	v_mfma_f32_16x16x32_bf16 v[52:55], v[192:195], v[154:157], v[52:55]
	v_mfma_f32_16x16x32_bf16 v[48:51], v[200:203], v[154:157], v[48:51]
	v_mfma_f32_16x16x32_bf16 v[36:39], v[192:195], v[168:171], v[36:39]
	v_mfma_f32_16x16x32_bf16 v[32:35], v[200:203], v[168:171], v[32:35]
	v_mfma_f32_16x16x32_bf16 v[16:19], v[192:195], v[176:179], v[16:19]
	v_mfma_f32_16x16x32_bf16 v[8:11], v[200:203], v[176:179], v[8:11]
	v_mfma_f32_16x16x32_bf16 v[4:7], v[192:195], v[184:187], v[4:7]
	v_mfma_f32_16x16x32_bf16 v[0:3], v[200:203], v[184:187], v[0:3]
	v_mfma_f32_16x16x32_bf16 v[52:55], v[196:199], v[164:167], v[52:55]
	v_mfma_f32_16x16x32_bf16 v[48:51], v[204:207], v[164:167], v[48:51]
	v_mfma_f32_16x16x32_bf16 v[36:39], v[196:199], v[172:175], v[36:39]
	v_mfma_f32_16x16x32_bf16 v[32:35], v[204:207], v[172:175], v[32:35]
	v_mfma_f32_16x16x32_bf16 v[16:19], v[196:199], v[180:183], v[16:19]
	v_mfma_f32_16x16x32_bf16 v[8:11], v[204:207], v[180:183], v[8:11]
	v_mfma_f32_16x16x32_bf16 v[4:7], v[196:199], v[188:191], v[4:7]
	v_mfma_f32_16x16x32_bf16 v[0:3], v[204:207], v[188:191], v[0:3]
	s_add_i32 s7, s7, 2
	s_addk_i32 s57, 0x100
	s_addk_i32 s44, 0x100
	s_cmp_gt_u32 s7, 29
	s_barrier
	s_cbranch_scc0 .LBB0_42
	s_lshl_b32 s0, s66, 8
	v_mov_b32_e32 v128, v161
	v_mov_b32_e32 v129, v160
	s_add_i32 s0, s0, s67
	s_and_b64 vcc, exec, s[18:19]
	v_add_u32_e32 v156, s0, v129
	s_lshl_b32 s0, s46, 8
	s_or_b32 s0, s0, s83
	v_lshl_add_u32 v128, v128, 3, s0
	v_ashrrev_i32_e32 v157, 31, v156
	v_ashrrev_i32_e32 v129, 31, v128
	v_lshlrev_b64 v[212:213], 13, v[156:157]
	v_lshl_add_u64 v[130:131], s[8:9], 0, v[212:213]
	v_lshlrev_b64 v[154:155], 2, v[128:129]
	v_lshl_add_u64 v[128:129], v[130:131], 0, v[154:155]
	global_load_dwordx4 v[164:167], v[128:129], off offset:16
	global_load_dwordx4 v[168:171], v[128:129], off
	global_load_dwordx4 v[172:175], v[128:129], off offset:528
	global_load_dwordx4 v[176:179], v[128:129], off offset:512
	v_add_u32_e32 v128, 16, v156
	v_ashrrev_i32_e32 v129, 31, v128
	v_lshlrev_b64 v[214:215], 13, v[128:129]
	v_lshl_add_u64 v[128:129], s[8:9], 0, v[214:215]
	v_lshl_add_u64 v[128:129], v[128:129], 0, v[154:155]
	global_load_dwordx4 v[180:183], v[128:129], off offset:16
	global_load_dwordx4 v[184:187], v[128:129], off
	global_load_dwordx4 v[188:191], v[128:129], off offset:528
	global_load_dwordx4 v[192:195], v[128:129], off offset:512
	v_add_u32_e32 v128, 32, v156
	v_ashrrev_i32_e32 v129, 31, v128
	v_lshlrev_b64 v[216:217], 13, v[128:129]
	v_lshl_add_u64 v[128:129], s[8:9], 0, v[216:217]
	v_lshl_add_u64 v[128:129], v[128:129], 0, v[154:155]
	global_load_dwordx4 v[196:199], v[128:129], off offset:16
	global_load_dwordx4 v[200:203], v[128:129], off
	global_load_dwordx4 v[204:207], v[128:129], off offset:528
	global_load_dwordx4 v[208:211], v[128:129], off offset:512
	v_add_u32_e32 v128, 48, v156
	v_ashrrev_i32_e32 v129, 31, v128
	v_lshlrev_b64 v[158:159], 13, v[128:129]
	v_lshl_add_u64 v[128:129], s[8:9], 0, v[158:159]
	v_lshl_add_u64 v[136:137], v[128:129], 0, v[154:155]
	global_load_dwordx4 v[132:135], v[136:137], off offset:16
	global_load_dwordx4 v[140:143], v[136:137], off
	global_load_dwordx4 v[128:131], v[136:137], off offset:528
	s_nop 0
	global_load_dwordx4 v[136:139], v[136:137], off offset:512
	v_lshl_add_u64 v[212:213], s[16:17], 0, v[212:213]
	s_mov_b32 s46, s22
	s_mov_b32 s66, s20
	s_mov_b64 s[68:69], s[64:65]
	s_mov_b64 s[70:71], s[62:63]
	s_movk_i32 s54, 0x4000
	s_movk_i32 s55, 0x6000
	v_readlane_b32 s0, v255, 23
	s_cmpk_gt_u32 s0, 0xff
	s_cbranch_scc1 .Lds_out_x
	s_barrier

; #define G_STAGE(bufoff, gbase, voff) do { _Pragma("unroll") for (int _i = 0; _i < 2; ++_i) \
;         __builtin_amdgcn_global_load_lds((const unsigned*)((const char*)(gbase) + (voff)[_i]), (LAS unsigned*)(lds + (bufoff) + ldsw + _i * 8192), 16, 0, 0); } while (0)
; #define G_LDA(dst, b, h) do { _Pragma("unroll") for (int m = 0; m < 4; ++m) _Pragma("unroll") for (int k = 0; k < 2; ++k) dst[m][k] = *(const LAS bf16x8*)(lds + G_SA(b, h) + aoff + m * 2048 + k * 1024); } while (0)
; #define G_LDB(dst, b, h) do { _Pragma("unroll") for (int n = 0; n < 2; ++n) _Pragma("unroll") for (int k = 0; k < 2; ++k) dst[n][k] = *(const LAS bf16x8*)(lds + G_SB(b, h) + boff + n * 2048 + k * 1024); } while (0)
; #define G_MMA(ai, bj, At, Bt) do { __builtin_amdgcn_s_setprio(1); _Pragma("unroll") for (int m = 0; m < 4; ++m) _Pragma("unroll") for (int n = 0; n < 2; ++n) _Pragma("unroll") for (int k = 0; k < 2; ++k) \
;         acc[ai][bj][m][n] = __builtin_amdgcn_mfma_f32_16x16x32_bf16(Bt[n][k], At[m][k], acc[ai][bj][m][n], 0, 0, 0); __builtin_amdgcn_s_setprio(0); } while (0)
; #define G_WAIT_V(n) asm volatile("s_waitcnt vmcnt(" #n ")" ::: "memory")
; #define G_WAIT_L(n) asm volatile("s_waitcnt lgkmcnt(" #n ")" ::: "memory")
; #define G_BAR __builtin_amdgcn_s_barrier()
; #define G_SCHED __builtin_amdgcn_sched_barrier(0)
; template <class J>
; DI void gemm_phase(LAS unsigned char* lds, const J& job) {
;     ...
;       const bool last = (t == nt - 2);
;       const char* a1 = cA + G_KT(t + 1);
;       const char* a2 = last ? nA + G_KT(0) : cA + G_KT(t + 2); const char* b2 = last ? nB + G_KT(0) : cB + G_KT(t + 2);
;       const char* a3 = last ? nA + G_KT(1) : cA + G_KT(t + 3); const char* b3 = last ? nB + G_KT(1) : cB + G_KT(t + 3);
;       G_LDB(B0, 0, 0); G_SCHED; G_LDA(At, 0, 0); G_STAGE(G_SA(1, 1), a1 + hstepA, voffA);
;       G_WAIT_L(8); G_BAR; G_WAIT_L(0); G_MMA(0, 0, At, B0); G_BAR; G_SCHED;
;       G_LDB(B1, 0, 1); G_STAGE(G_SB(0, 0), b2, voffB);
;       G_BAR; G_WAIT_L(0); G_MMA(0, 1, At, B1); G_BAR;
;       G_LDA(At, 0, 1); G_STAGE(G_SA(0, 0), a2, voffA);
;       G_BAR; G_WAIT_L(0); G_MMA(1, 0, At, B0); G_BAR; G_SCHED;
;       G_STAGE(G_SB(0, 1), b2 + hstepB, voffB);
;       G_WAIT_V(6); G_BAR; G_MMA(1, 1, At, B1); G_BAR;
.LBB0_74:
	s_add_i32 s1, s56, 0xffffff80
	s_and_b32 s0, s7, 0xf80
	s_and_b32 s1, s1, 0xf00
	s_add_u32 s57, s68, s1
	s_addc_u32 s70, s69, 0
	s_add_u32 s1, s66, s1
	s_addc_u32 s71, s67, 0
	s_and_b32 s72, s56, 0xf80
	s_add_u32 s80, s68, s72
	s_addc_u32 s73, s69, 0
	s_add_u32 s38, s66, s72
	s_addc_u32 s2, s67, 0
	s_cmp_eq_u32 s6, 28
	s_cselect_b32 s75, s46, s70
	s_cselect_b32 s74, s45, s57
	s_cselect_b32 s77, vcc_lo, s71
	s_cselect_b32 s76, s47, s1
	s_cselect_b32 s73, s97, s73
	s_cselect_b32 s72, s33, s80
	s_cselect_b32 s71, s5, s2
	s_cselect_b32 s70, vcc_hi, s38
	s_add_i32 s2, s84, 0x100
	v_add_u32_e32 v100, s2, v248
	ds_read_b128 v[84:87], v100
	ds_read_b128 v[88:91], v100 offset:1024
	ds_read_b128 v[96:99], v100 offset:2048
	ds_read_b128 v[100:103], v100 offset:3072
	s_add_u32 s0, s19, s0
	s_addc_u32 s1, s21, 0
	v_lshl_add_u64 v[186:187], s[0:1], 0, v[148:149]
	s_add_i32 m0, s14, 0xc000
	ds_read_b128 v[154:157], v249
	ds_read_b128 v[158:161], v249 offset:1024
	ds_read_b128 v[162:165], v249 offset:2048
	ds_read_b128 v[166:169], v249 offset:3072
	ds_read_b128 v[170:173], v249 offset:4096
	ds_read_b128 v[174:177], v249 offset:5120
	ds_read_b128 v[178:181], v249 offset:6144
	ds_read_b128 v[182:185], v249 offset:7168
	global_load_lds_dwordx4 v[186:187], off
	v_lshl_add_u64 v[186:187], s[0:1], 0, v[150:151]
	s_add_i32 m0, s14, 0xe000
	s_nop 0
	global_load_lds_dwordx4 v[186:187], off
	s_waitcnt lgkmcnt(8)
	s_barrier
	s_waitcnt lgkmcnt(0)
	v_mfma_f32_16x16x32_bf16 v[140:143], v[84:87], v[154:157], v[140:143]
	v_mfma_f32_16x16x32_bf16 v[136:139], v[96:99], v[154:157], v[136:139]
	v_mfma_f32_16x16x32_bf16 v[124:127], v[84:87], v[162:165], v[124:127]
	v_mfma_f32_16x16x32_bf16 v[120:123], v[96:99], v[162:165], v[120:123]
	v_mfma_f32_16x16x32_bf16 v[108:111], v[84:87], v[170:173], v[108:111]
	v_mfma_f32_16x16x32_bf16 v[104:107], v[96:99], v[170:173], v[104:107]
	v_mfma_f32_16x16x32_bf16 v[76:79], v[84:87], v[178:181], v[76:79]
	v_mfma_f32_16x16x32_bf16 v[72:75], v[96:99], v[178:181], v[72:75]
	v_mfma_f32_16x16x32_bf16 v[140:143], v[88:91], v[158:161], v[140:143]
	v_mfma_f32_16x16x32_bf16 v[136:139], v[100:103], v[158:161], v[136:139]
	v_mfma_f32_16x16x32_bf16 v[124:127], v[88:91], v[166:169], v[124:127]
	v_mfma_f32_16x16x32_bf16 v[120:123], v[100:103], v[166:169], v[120:123]
	v_mfma_f32_16x16x32_bf16 v[108:111], v[88:91], v[174:177], v[108:111]
	v_mfma_f32_16x16x32_bf16 v[104:107], v[100:103], v[174:177], v[104:107]
	v_mfma_f32_16x16x32_bf16 v[76:79], v[88:91], v[182:185], v[76:79]
	v_mfma_f32_16x16x32_bf16 v[72:75], v[100:103], v[182:185], v[72:75]
	s_barrier
	s_add_i32 s38, s85, 0x100
	s_add_i32 s0, s2, s78
	v_add_u32_e32 v198, s38, v248
	v_lshl_add_u64 v[202:203], s[76:77], 0, v[146:147]
	s_mov_b32 m0, s0
	ds_read_b128 v[186:189], v198
	ds_read_b128 v[190:193], v198 offset:1024
	ds_read_b128 v[194:197], v198 offset:2048
	ds_read_b128 v[198:201], v198 offset:3072
	global_load_lds_dwordx4 v[202:203], off
	v_lshl_add_u64 v[202:203], s[76:77], 0, v[152:153]
	s_add_i32 m0, s0, 0x2000
	s_nop 0
	global_load_lds_dwordx4 v[202:203], off
	s_barrier
	s_waitcnt lgkmcnt(0)
	v_mfma_f32_16x16x32_bf16 v[132:135], v[186:189], v[154:157], v[132:135]
	v_mfma_f32_16x16x32_bf16 v[128:131], v[194:197], v[154:157], v[128:131]
	v_mfma_f32_16x16x32_bf16 v[116:119], v[186:189], v[162:165], v[116:119]
	v_mfma_f32_16x16x32_bf16 v[112:115], v[194:197], v[162:165], v[112:115]
	v_mfma_f32_16x16x32_bf16 v[92:95], v[186:189], v[170:173], v[92:95]
	v_mfma_f32_16x16x32_bf16 v[80:83], v[194:197], v[170:173], v[80:83]
	v_mfma_f32_16x16x32_bf16 v[68:71], v[186:189], v[178:181], v[68:71]
	v_mfma_f32_16x16x32_bf16 v[64:67], v[194:197], v[178:181], v[64:67]
	v_mfma_f32_16x16x32_bf16 v[132:135], v[190:193], v[158:161], v[132:135]
	v_mfma_f32_16x16x32_bf16 v[128:131], v[198:201], v[158:161], v[128:131]
	v_mfma_f32_16x16x32_bf16 v[116:119], v[190:193], v[166:169], v[116:119]
	v_mfma_f32_16x16x32_bf16 v[112:115], v[198:201], v[166:169], v[112:115]
	v_mfma_f32_16x16x32_bf16 v[92:95], v[190:193], v[174:177], v[92:95]
	v_mfma_f32_16x16x32_bf16 v[80:83], v[198:201], v[174:177], v[80:83]
	v_mfma_f32_16x16x32_bf16 v[68:71], v[190:193], v[182:185], v[68:71]
	v_mfma_f32_16x16x32_bf16 v[64:67], v[198:201], v[182:185], v[64:67]
	s_barrier
	s_mov_b32 m0, s14
	v_lshl_add_u64 v[202:203], s[74:75], 0, v[148:149]
	ds_read_b128 v[154:157], v249 offset:16384
	ds_read_b128 v[158:161], v249 offset:17408
	ds_read_b128 v[162:165], v249 offset:18432
	ds_read_b128 v[166:169], v249 offset:19456
	ds_read_b128 v[170:173], v249 offset:20480
	ds_read_b128 v[174:177], v249 offset:21504
	ds_read_b128 v[178:181], v249 offset:22528
	ds_read_b128 v[182:185], v249 offset:23552
	global_load_lds_dwordx4 v[202:203], off
	v_lshl_add_u64 v[202:203], s[74:75], 0, v[150:151]
	s_mov_b32 m0, s15
	s_nop 0
	global_load_lds_dwordx4 v[202:203], off
	s_barrier
	s_waitcnt lgkmcnt(0)
	v_mfma_f32_16x16x32_bf16 v[60:63], v[84:87], v[154:157], v[60:63]
	v_mfma_f32_16x16x32_bf16 v[56:59], v[96:99], v[154:157], v[56:59]
	v_mfma_f32_16x16x32_bf16 v[44:47], v[84:87], v[162:165], v[44:47]
	v_mfma_f32_16x16x32_bf16 v[40:43], v[96:99], v[162:165], v[40:43]
	v_mfma_f32_16x16x32_bf16 v[28:31], v[84:87], v[170:173], v[28:31]
	v_mfma_f32_16x16x32_bf16 v[24:27], v[96:99], v[170:173], v[24:27]
	v_mfma_f32_16x16x32_bf16 v[12:15], v[84:87], v[178:181], v[12:15]
	v_mfma_f32_16x16x32_bf16 v[8:11], v[96:99], v[178:181], v[8:11]
	v_mfma_f32_16x16x32_bf16 v[60:63], v[88:91], v[158:161], v[60:63]
	v_mfma_f32_16x16x32_bf16 v[56:59], v[100:103], v[158:161], v[56:59]
	v_mfma_f32_16x16x32_bf16 v[44:47], v[88:91], v[166:169], v[44:47]
	v_mfma_f32_16x16x32_bf16 v[40:43], v[100:103], v[166:169], v[40:43]
	v_mfma_f32_16x16x32_bf16 v[28:31], v[88:91], v[174:177], v[28:31]
	v_mfma_f32_16x16x32_bf16 v[24:27], v[100:103], v[174:177], v[24:27]
	v_mfma_f32_16x16x32_bf16 v[12:15], v[88:91], v[182:185], v[12:15]
	v_mfma_f32_16x16x32_bf16 v[8:11], v[100:103], v[182:185], v[8:11]
	s_barrier
; #define G_STAGE(bufoff, gbase, voff) do { _Pragma("unroll") for (int _i = 0; _i < 2; ++_i) \
;         __builtin_amdgcn_global_load_lds((const unsigned*)((const char*)(gbase) + (voff)[_i]), (LAS unsigned*)(lds + (bufoff) + ldsw + _i * 8192), 16, 0, 0); } while (0)
; #define G_LDA(dst, b, h) do { _Pragma("unroll") for (int m = 0; m < 4; ++m) _Pragma("unroll") for (int k = 0; k < 2; ++k) dst[m][k] = *(const LAS bf16x8*)(lds + G_SA(b, h) + aoff + m * 2048 + k * 1024); } while (0)
; #define G_LDB(dst, b, h) do { _Pragma("unroll") for (int n = 0; n < 2; ++n) _Pragma("unroll") for (int k = 0; k < 2; ++k) dst[n][k] = *(const LAS bf16x8*)(lds + G_SB(b, h) + boff + n * 2048 + k * 1024); } while (0)
; #define G_MMA(ai, bj, At, Bt) do { __builtin_amdgcn_s_setprio(1); _Pragma("unroll") for (int m = 0; m < 4; ++m) _Pragma("unroll") for (int n = 0; n < 2; ++n) _Pragma("unroll") for (int k = 0; k < 2; ++k) \
;         acc[ai][bj][m][n] = __builtin_amdgcn_mfma_f32_16x16x32_bf16(Bt[n][k], At[m][k], acc[ai][bj][m][n], 0, 0, 0); __builtin_amdgcn_s_setprio(0); } while (0)
; #define G_WAIT_V(n) asm volatile("s_waitcnt vmcnt(" #n ")" ::: "memory")
; #define G_WAIT_L(n) asm volatile("s_waitcnt lgkmcnt(" #n ")" ::: "memory")
; #define G_BAR __builtin_amdgcn_s_barrier()
; #define G_SCHED __builtin_amdgcn_sched_barrier(0)
; template <class J>
; DI void gemm_phase(LAS unsigned char* lds, const J& job) {
;     ...
;       G_STAGE(G_SB(0, 1), b2 + hstepB, voffB);
;       G_WAIT_V(6); G_BAR; G_MMA(1, 1, At, B1); G_BAR;
;       G_LDB(B0, 1, 0); G_SCHED; G_LDA(At, 1, 0); G_STAGE(G_SA(0, 1), a2 + hstepA, voffA);
;       G_WAIT_L(8); G_BAR; G_WAIT_L(0); G_MMA(0, 0, At, B0); G_BAR; G_SCHED;
;       G_LDB(B1, 1, 1); G_STAGE(G_SB(1, 0), b3, voffB);
;       G_BAR; G_WAIT_L(0); G_MMA(0, 1, At, B1); G_BAR;
;       G_LDA(At, 1, 1); G_STAGE(G_SA(1, 0), a3, voffA);
;       G_BAR; G_WAIT_L(0); G_MMA(1, 0, At, B0); G_BAR; G_SCHED;
	s_add_u32 s0, s76, 0x1000000
	s_addc_u32 s1, s77, 0
	s_add_i32 s2, s38, s78
	v_lshl_add_u64 v[84:85], s[0:1], 0, v[146:147]
	s_mov_b32 m0, s2
	s_nop 0
	global_load_lds_dwordx4 v[84:85], off
	v_lshl_add_u64 v[84:85], s[0:1], 0, v[152:153]
	s_add_i32 m0, s2, 0x2000
	s_nop 0
	global_load_lds_dwordx4 v[84:85], off
	s_waitcnt vmcnt(6)
	s_barrier
	v_mfma_f32_16x16x32_bf16 v[52:55], v[186:189], v[154:157], v[52:55]
	v_mfma_f32_16x16x32_bf16 v[48:51], v[194:197], v[154:157], v[48:51]
	v_mfma_f32_16x16x32_bf16 v[36:39], v[186:189], v[162:165], v[36:39]
	v_mfma_f32_16x16x32_bf16 v[32:35], v[194:197], v[162:165], v[32:35]
	v_mfma_f32_16x16x32_bf16 v[20:23], v[186:189], v[170:173], v[20:23]
	v_mfma_f32_16x16x32_bf16 v[16:19], v[194:197], v[170:173], v[16:19]
	v_mfma_f32_16x16x32_bf16 v[4:7], v[186:189], v[178:181], v[4:7]
	v_mfma_f32_16x16x32_bf16 v[0:3], v[194:197], v[178:181], v[0:3]
	v_mfma_f32_16x16x32_bf16 v[52:55], v[190:193], v[158:161], v[52:55]
	v_mfma_f32_16x16x32_bf16 v[48:51], v[198:201], v[158:161], v[48:51]
	v_mfma_f32_16x16x32_bf16 v[36:39], v[190:193], v[166:169], v[36:39]
	v_mfma_f32_16x16x32_bf16 v[32:35], v[198:201], v[166:169], v[32:35]
	v_mfma_f32_16x16x32_bf16 v[20:23], v[190:193], v[174:177], v[20:23]
	v_mfma_f32_16x16x32_bf16 v[16:19], v[198:201], v[174:177], v[16:19]
	v_mfma_f32_16x16x32_bf16 v[4:7], v[190:193], v[182:185], v[4:7]
	v_mfma_f32_16x16x32_bf16 v[0:3], v[198:201], v[182:185], v[0:3]
	s_barrier
	s_add_i32 s2, s88, 0x100
	v_add_u32_e32 v100, s2, v248
	ds_read_b128 v[84:87], v100
	ds_read_b128 v[88:91], v100 offset:1024
	ds_read_b128 v[96:99], v100 offset:2048
	ds_read_b128 v[100:103], v100 offset:3072
	s_add_u32 s0, s74, 0x80000
	s_addc_u32 s1, s75, 0
	s_mov_b32 m0, s83
	v_lshl_add_u64 v[186:187], s[0:1], 0, v[148:149]
	ds_read_b128 v[154:157], v249 offset:32768
	ds_read_b128 v[158:161], v249 offset:33792
	ds_read_b128 v[162:165], v249 offset:34816
	ds_read_b128 v[166:169], v249 offset:35840
	ds_read_b128 v[170:173], v249 offset:36864
	ds_read_b128 v[174:177], v249 offset:37888
	ds_read_b128 v[178:181], v249 offset:38912
	ds_read_b128 v[182:185], v249 offset:39936
	global_load_lds_dwordx4 v[186:187], off
	v_lshl_add_u64 v[186:187], s[0:1], 0, v[150:151]
	s_mov_b32 m0, s36
	s_nop 0
	global_load_lds_dwordx4 v[186:187], off
	s_waitcnt lgkmcnt(8)
	s_barrier
	s_waitcnt lgkmcnt(0)
	v_mfma_f32_16x16x32_bf16 v[140:143], v[84:87], v[154:157], v[140:143]
	v_mfma_f32_16x16x32_bf16 v[136:139], v[96:99], v[154:157], v[136:139]
	v_mfma_f32_16x16x32_bf16 v[124:127], v[84:87], v[162:165], v[124:127]
	v_mfma_f32_16x16x32_bf16 v[120:123], v[96:99], v[162:165], v[120:123]
	v_mfma_f32_16x16x32_bf16 v[108:111], v[84:87], v[170:173], v[108:111]
	v_mfma_f32_16x16x32_bf16 v[104:107], v[96:99], v[170:173], v[104:107]
	v_mfma_f32_16x16x32_bf16 v[76:79], v[84:87], v[178:181], v[76:79]
	v_mfma_f32_16x16x32_bf16 v[72:75], v[96:99], v[178:181], v[72:75]
	v_mfma_f32_16x16x32_bf16 v[140:143], v[88:91], v[158:161], v[140:143]
	v_mfma_f32_16x16x32_bf16 v[136:139], v[100:103], v[158:161], v[136:139]
	v_mfma_f32_16x16x32_bf16 v[124:127], v[88:91], v[166:169], v[124:127]
	v_mfma_f32_16x16x32_bf16 v[120:123], v[100:103], v[166:169], v[120:123]
	v_mfma_f32_16x16x32_bf16 v[108:111], v[88:91], v[174:177], v[108:111]
	v_mfma_f32_16x16x32_bf16 v[104:107], v[100:103], v[174:177], v[104:107]
	v_mfma_f32_16x16x32_bf16 v[76:79], v[88:91], v[182:185], v[76:79]
	v_mfma_f32_16x16x32_bf16 v[72:75], v[100:103], v[182:185], v[72:75]
	s_barrier
	s_add_i32 s38, s89, 0x100
	s_add_i32 s0, s2, s78
	v_add_u32_e32 v198, s38, v248
	v_lshl_add_u64 v[202:203], s[70:71], 0, v[146:147]
	s_mov_b32 m0, s0
	ds_read_b128 v[186:189], v198
	ds_read_b128 v[190:193], v198 offset:1024
	ds_read_b128 v[194:197], v198 offset:2048
	ds_read_b128 v[198:201], v198 offset:3072
	global_load_lds_dwordx4 v[202:203], off
	v_lshl_add_u64 v[202:203], s[70:71], 0, v[152:153]
	s_add_i32 m0, s0, 0x2000
	s_nop 0
	global_load_lds_dwordx4 v[202:203], off
	s_barrier
	s_waitcnt lgkmcnt(0)
	v_mfma_f32_16x16x32_bf16 v[132:135], v[186:189], v[154:157], v[132:135]
	v_mfma_f32_16x16x32_bf16 v[128:131], v[194:197], v[154:157], v[128:131]
	v_mfma_f32_16x16x32_bf16 v[116:119], v[186:189], v[162:165], v[116:119]
	v_mfma_f32_16x16x32_bf16 v[112:115], v[194:197], v[162:165], v[112:115]
	v_mfma_f32_16x16x32_bf16 v[92:95], v[186:189], v[170:173], v[92:95]
	v_mfma_f32_16x16x32_bf16 v[80:83], v[194:197], v[170:173], v[80:83]
	v_mfma_f32_16x16x32_bf16 v[68:71], v[186:189], v[178:181], v[68:71]
	v_mfma_f32_16x16x32_bf16 v[64:67], v[194:197], v[178:181], v[64:67]
	v_mfma_f32_16x16x32_bf16 v[132:135], v[190:193], v[158:161], v[132:135]
	v_mfma_f32_16x16x32_bf16 v[128:131], v[198:201], v[158:161], v[128:131]
	v_mfma_f32_16x16x32_bf16 v[116:119], v[190:193], v[166:169], v[116:119]
	v_mfma_f32_16x16x32_bf16 v[112:115], v[198:201], v[166:169], v[112:115]
	v_mfma_f32_16x16x32_bf16 v[92:95], v[190:193], v[174:177], v[92:95]
	v_mfma_f32_16x16x32_bf16 v[80:83], v[198:201], v[174:177], v[80:83]
	v_mfma_f32_16x16x32_bf16 v[68:71], v[190:193], v[182:185], v[68:71]
	v_mfma_f32_16x16x32_bf16 v[64:67], v[198:201], v[182:185], v[64:67]
	s_barrier
	s_mov_b32 m0, s24
	v_lshl_add_u64 v[202:203], s[72:73], 0, v[148:149]
	ds_read_b128 v[154:157], v249 offset:49152
	ds_read_b128 v[158:161], v249 offset:50176
	ds_read_b128 v[162:165], v249 offset:51200
	ds_read_b128 v[166:169], v249 offset:52224
	ds_read_b128 v[170:173], v249 offset:53248
	ds_read_b128 v[174:177], v249 offset:54272
	ds_read_b128 v[178:181], v249 offset:55296
	ds_read_b128 v[182:185], v249 offset:56320
	global_load_lds_dwordx4 v[202:203], off
	v_lshl_add_u64 v[202:203], s[72:73], 0, v[150:151]
	s_mov_b32 m0, s25
	s_nop 0
	global_load_lds_dwordx4 v[202:203], off
	s_barrier
; #define G_STAGE(bufoff, gbase, voff) do { _Pragma("unroll") for (int _i = 0; _i < 2; ++_i) \
;         __builtin_amdgcn_global_load_lds((const unsigned*)((const char*)(gbase) + (voff)[_i]), (LAS unsigned*)(lds + (bufoff) + ldsw + _i * 8192), 16, 0, 0); } while (0)
; #define G_MMA(ai, bj, At, Bt) do { __builtin_amdgcn_s_setprio(1); _Pragma("unroll") for (int m = 0; m < 4; ++m) _Pragma("unroll") for (int n = 0; n < 2; ++n) _Pragma("unroll") for (int k = 0; k < 2; ++k) \
;         acc[ai][bj][m][n] = __builtin_amdgcn_mfma_f32_16x16x32_bf16(Bt[n][k], At[m][k], acc[ai][bj][m][n], 0, 0, 0); __builtin_amdgcn_s_setprio(0); } while (0)
; #define G_WAIT_V(n) asm volatile("s_waitcnt vmcnt(" #n ")" ::: "memory")
; #define G_WAIT_L(n) asm volatile("s_waitcnt lgkmcnt(" #n ")" ::: "memory")
; #define G_BAR __builtin_amdgcn_s_barrier()
; #define G_SCHED __builtin_amdgcn_sched_barrier(0)
; template <class J>
; DI void gemm_phase(LAS unsigned char* lds, const J& job) {
;     ...
;       G_BAR; G_WAIT_L(0); G_MMA(1, 0, At, B0); G_BAR; G_SCHED;
;       G_STAGE(G_SB(1, 1), b3 + hstepB, voffB);
;       G_WAIT_V(6); G_BAR; G_MMA(1, 1, At, B1); G_BAR;
	s_waitcnt lgkmcnt(0)
	v_mfma_f32_16x16x32_bf16 v[60:63], v[84:87], v[154:157], v[60:63]
	v_mfma_f32_16x16x32_bf16 v[56:59], v[96:99], v[154:157], v[56:59]
	v_mfma_f32_16x16x32_bf16 v[44:47], v[84:87], v[162:165], v[44:47]
	v_mfma_f32_16x16x32_bf16 v[40:43], v[96:99], v[162:165], v[40:43]
	v_mfma_f32_16x16x32_bf16 v[28:31], v[84:87], v[170:173], v[28:31]
	v_mfma_f32_16x16x32_bf16 v[24:27], v[96:99], v[170:173], v[24:27]
	v_mfma_f32_16x16x32_bf16 v[12:15], v[84:87], v[178:181], v[12:15]
	v_mfma_f32_16x16x32_bf16 v[8:11], v[96:99], v[178:181], v[8:11]
	v_mfma_f32_16x16x32_bf16 v[60:63], v[88:91], v[158:161], v[60:63]
	v_mfma_f32_16x16x32_bf16 v[56:59], v[100:103], v[158:161], v[56:59]
	v_mfma_f32_16x16x32_bf16 v[44:47], v[88:91], v[166:169], v[44:47]
	v_mfma_f32_16x16x32_bf16 v[40:43], v[100:103], v[166:169], v[40:43]
	v_mfma_f32_16x16x32_bf16 v[28:31], v[88:91], v[174:177], v[28:31]
	v_mfma_f32_16x16x32_bf16 v[24:27], v[100:103], v[174:177], v[24:27]
	v_mfma_f32_16x16x32_bf16 v[12:15], v[88:91], v[182:185], v[12:15]
	v_mfma_f32_16x16x32_bf16 v[8:11], v[100:103], v[182:185], v[8:11]
	s_barrier
	s_add_u32 s0, s70, 0x1000000
	s_addc_u32 s1, s71, 0
	s_add_i32 s2, s38, s78
	v_lshl_add_u64 v[84:85], s[0:1], 0, v[146:147]
	s_mov_b32 m0, s2
	s_nop 0
	global_load_lds_dwordx4 v[84:85], off
	v_lshl_add_u64 v[84:85], s[0:1], 0, v[152:153]
	s_add_i32 m0, s2, 0x2000
	s_nop 0
	global_load_lds_dwordx4 v[84:85], off
	s_waitcnt vmcnt(6)
	s_barrier
	v_mfma_f32_16x16x32_bf16 v[52:55], v[186:189], v[154:157], v[52:55]
	v_mfma_f32_16x16x32_bf16 v[48:51], v[194:197], v[154:157], v[48:51]
	v_mfma_f32_16x16x32_bf16 v[36:39], v[186:189], v[162:165], v[36:39]
	v_mfma_f32_16x16x32_bf16 v[32:35], v[194:197], v[162:165], v[32:35]
	v_mfma_f32_16x16x32_bf16 v[20:23], v[186:189], v[170:173], v[20:23]
	v_mfma_f32_16x16x32_bf16 v[16:19], v[194:197], v[170:173], v[16:19]
	v_mfma_f32_16x16x32_bf16 v[4:7], v[186:189], v[178:181], v[4:7]
	v_mfma_f32_16x16x32_bf16 v[0:3], v[194:197], v[178:181], v[0:3]
	v_mfma_f32_16x16x32_bf16 v[52:55], v[190:193], v[158:161], v[52:55]
	v_mfma_f32_16x16x32_bf16 v[48:51], v[198:201], v[158:161], v[48:51]
	v_mfma_f32_16x16x32_bf16 v[36:39], v[190:193], v[166:169], v[36:39]
	v_mfma_f32_16x16x32_bf16 v[32:35], v[198:201], v[166:169], v[32:35]
	v_mfma_f32_16x16x32_bf16 v[20:23], v[190:193], v[174:177], v[20:23]
	v_mfma_f32_16x16x32_bf16 v[16:19], v[198:201], v[174:177], v[16:19]
	v_mfma_f32_16x16x32_bf16 v[4:7], v[190:193], v[182:185], v[4:7]
	v_mfma_f32_16x16x32_bf16 v[0:3], v[198:201], v[182:185], v[0:3]
	s_add_i32 s6, s6, 2
	s_addk_i32 s56, 0x100
	s_addk_i32 s7, 0x100
	s_cmp_gt_u32 s6, 29
	s_barrier
	s_cbranch_scc0 .LBB0_74
;   DI void epi(const Acc& acc, const Unit& u, int wr, int wc, int fr, int fq) const {
;     const int cc = u.pn * 64 + 16 * wc + 4 * fq;
;     u32x2 zz[2][4][4];
; #pragma unroll
;     for (int ai = 0; ai < 2; ++ai)
; #pragma unroll
;       for (int m = 0; m < 4; ++m) {
;         const u16* zr = Z + (size_t)(u.pm * 256 + ai * HALF + wr * 64 + m * 16 + fr) * NGATE + cc;
; #pragma unroll
;         for (int br = 0; br < 4; ++br) zz[ai][m][br] = *(const u32x2*)(zr + br * 2048);
;       }
;     f32x4 bg[4];
; #pragma unroll
;     for (int br = 0; br < 4; ++br) bg[br] = *(const f32x4*)(bgate + br * 2048 + cc);
	v_mov_b32_e32 v84, v247
	v_mov_b32_e32 v85, v246
	s_lshl_b32 s0, s44, 6
	s_or_b32 s0, s0, s96
	v_lshl_add_u32 v84, v84, 2, s0
	s_lshl_b32 s0, s64, 8
	s_add_i32 s0, s0, s37
	v_add_u32_e32 v224, s0, v85
	v_ashrrev_i32_e32 v85, 31, v84
	v_lshlrev_b64 v[154:155], 1, v[84:85]
	v_ashrrev_i32_e32 v225, 31, v224
	v_lshl_add_u64 v[86:87], s[26:27], 0, v[154:155]
	v_lshlrev_b64 v[88:89], 14, v[224:225]
	v_lshl_add_u64 v[88:89], v[86:87], 0, v[88:89]
	v_add_co_u32_e32 v90, vcc, s82, v88
	v_add_u32_e32 v212, 16, v224
	s_nop 0
	v_addc_co_u32_e32 v91, vcc, 0, v89, vcc
	v_ashrrev_i32_e32 v213, 31, v212
	v_add_co_u32_e32 v96, vcc, s92, v88
	v_lshlrev_b64 v[98:99], 14, v[212:213]
	s_nop 0
	v_addc_co_u32_e32 v97, vcc, 0, v89, vcc
	v_lshl_add_u64 v[98:99], v[86:87], 0, v[98:99]
	v_add_co_u32_e32 v100, vcc, s82, v98
	v_add_u32_e32 v202, 32, v224
	s_nop 0
	v_addc_co_u32_e32 v101, vcc, 0, v99, vcc
	global_load_dwordx2 v[230:231], v[90:91], off offset:-4096
	global_load_dwordx2 v[226:227], v[90:91], off
	global_load_dwordx2 v[220:221], v[100:101], off offset:-4096
	global_load_dwordx2 v[214:215], v[100:101], off
	v_add_co_u32_e32 v90, vcc, s92, v98
	v_ashrrev_i32_e32 v203, 31, v202
	s_nop 0
	v_addc_co_u32_e32 v91, vcc, 0, v99, vcc
	global_load_dwordx2 v[232:233], v[88:89], off
	global_load_dwordx2 v[228:229], v[96:97], off
	global_load_dwordx2 v[222:223], v[98:99], off
	global_load_dwordx2 v[216:217], v[90:91], off
	v_lshlrev_b64 v[88:89], 14, v[202:203]
	v_lshl_add_u64 v[88:89], v[86:87], 0, v[88:89]
	v_add_co_u32_e32 v90, vcc, s82, v88
	v_add_u32_e32 v190, 48, v224
	s_nop 0
	v_addc_co_u32_e32 v91, vcc, 0, v89, vcc
	v_ashrrev_i32_e32 v191, 31, v190
	v_add_co_u32_e32 v96, vcc, s92, v88
	v_lshlrev_b64 v[98:99], 14, v[190:191]
	s_nop 0
	v_addc_co_u32_e32 v97, vcc, 0, v89, vcc
	v_lshl_add_u64 v[98:99], v[86:87], 0, v[98:99]
	v_add_co_u32_e32 v100, vcc, s82, v98
	v_add_u32_e32 v184, 0x80, v224
	s_nop 0
	v_addc_co_u32_e32 v101, vcc, 0, v99, vcc
	global_load_dwordx2 v[210:211], v[90:91], off offset:-4096
	global_load_dwordx2 v[206:207], v[90:91], off
	global_load_dwordx2 v[200:201], v[100:101], off offset:-4096
	global_load_dwordx2 v[192:193], v[100:101], off
	v_add_co_u32_e32 v90, vcc, s92, v98
	v_lshl_add_u64 v[84:85], v[84:85], 2, s[12:13]
	v_ashrrev_i32_e32 v185, 31, v184
	v_addc_co_u32_e32 v91, vcc, 0, v99, vcc
	global_load_dwordx4 v[100:103], v[84:85], off
	global_load_dwordx2 v[218:219], v[88:89], off
	global_load_dwordx2 v[208:209], v[96:97], off
	global_load_dwordx2 v[204:205], v[98:99], off
	global_load_dwordx2 v[198:199], v[90:91], off
	v_lshlrev_b64 v[88:89], 14, v[184:185]
	v_lshl_add_u64 v[88:89], v[86:87], 0, v[88:89]
	v_add_co_u32_e32 v90, vcc, s82, v88
	v_add_u32_e32 v174, 0x90, v224
	s_nop 0
	v_addc_co_u32_e32 v91, vcc, 0, v89, vcc
	v_add_co_u32_e32 v156, vcc, s92, v88
	v_ashrrev_i32_e32 v175, 31, v174
	s_nop 0
	v_addc_co_u32_e32 v157, vcc, 0, v89, vcc
	v_add_co_u32_e32 v96, vcc, s82, v84
	v_lshlrev_b64 v[158:159], 14, v[174:175]
	s_nop 0
	v_addc_co_u32_e32 v97, vcc, 0, v85, vcc
	global_load_dwordx4 v[96:99], v[96:97], off
	v_lshl_add_u64 v[158:159], v[86:87], 0, v[158:159]
	v_add_co_u32_e32 v160, vcc, s82, v158
	v_add_u32_e32 v164, 0xa0, v224
	s_nop 0
	v_addc_co_u32_e32 v161, vcc, 0, v159, vcc
	global_load_dwordx2 v[194:195], v[90:91], off offset:-4096
	global_load_dwordx2 v[186:187], v[90:91], off
	global_load_dwordx2 v[180:181], v[160:161], off offset:-4096
	global_load_dwordx2 v[176:177], v[160:161], off
	v_add_co_u32_e32 v90, vcc, s92, v158
	v_ashrrev_i32_e32 v165, 31, v164
	s_nop 0
	v_addc_co_u32_e32 v91, vcc, 0, v159, vcc
	global_load_dwordx2 v[196:197], v[88:89], off
	global_load_dwordx2 v[188:189], v[156:157], off
	global_load_dwordx2 v[182:183], v[158:159], off
	global_load_dwordx2 v[178:179], v[90:91], off
	v_lshlrev_b64 v[88:89], 14, v[164:165]
	v_lshl_add_u64 v[162:163], v[86:87], 0, v[88:89]
	v_add_co_u32_e32 v158, vcc, s82, v162
	v_add_u32_e32 v156, 0xb0, v224
	s_nop 0
	v_addc_co_u32_e32 v159, vcc, 0, v163, vcc
	v_add_co_u32_e32 v168, vcc, s92, v162
	v_ashrrev_i32_e32 v157, 31, v156
	s_nop 0
	v_addc_co_u32_e32 v169, vcc, 0, v163, vcc
	v_add_co_u32_e32 v88, vcc, s54, v84
	v_lshlrev_b64 v[160:161], 14, v[156:157]
	s_nop 0
	v_addc_co_u32_e32 v89, vcc, 0, v85, vcc
	global_load_dwordx4 v[88:91], v[88:89], off
	v_lshl_add_u64 v[250:251], v[86:87], 0, v[160:161]
	v_add_co_u32_e32 v86, vcc, s82, v250
	s_mov_b32 s44, s20
	s_nop 0
	v_addc_co_u32_e32 v87, vcc, 0, v251, vcc
	v_add_co_u32_e32 v84, vcc, s55, v84
	global_load_dwordx2 v[170:171], v[158:159], off offset:-4096
	global_load_dwordx2 v[166:167], v[158:159], off
	global_load_dwordx2 v[160:161], v[86:87], off offset:-4096
	s_nop 0
	global_load_dwordx2 v[158:159], v[86:87], off
	v_addc_co_u32_e32 v85, vcc, 0, v85, vcc
	global_load_dwordx4 v[84:87], v[84:85], off
	v_add_co_u32_e32 v252, vcc, s92, v250
	s_mov_b32 s64, s18
	s_nop 0
	v_addc_co_u32_e32 v253, vcc, 0, v251, vcc
	s_and_b64 vcc, exec, s[8:9]
	s_mov_b64 s[66:67], s[62:63]
	s_mov_b64 s[68:69], s[22:23]
	v_readlane_b32 s0, v255, 23
	s_cmpk_gt_u32 s0, 0xff
	s_cbranch_scc1 .Lds_gate_x
	s_barrier

; #define G_STAGE(bufoff, gbase, voff) do { _Pragma("unroll") for (int _i = 0; _i < 2; ++_i) \
;         __builtin_amdgcn_global_load_lds((const unsigned*)((const char*)(gbase) + (voff)[_i]), (LAS unsigned*)(lds + (bufoff) + ldsw + _i * 8192), 16, 0, 0); } while (0)
; #define G_LDA(dst, b, h) do { _Pragma("unroll") for (int m = 0; m < 4; ++m) _Pragma("unroll") for (int k = 0; k < 2; ++k) dst[m][k] = *(const LAS bf16x8*)(lds + G_SA(b, h) + aoff + m * 2048 + k * 1024); } while (0)
; #define G_LDB(dst, b, h) do { _Pragma("unroll") for (int n = 0; n < 2; ++n) _Pragma("unroll") for (int k = 0; k < 2; ++k) dst[n][k] = *(const LAS bf16x8*)(lds + G_SB(b, h) + boff + n * 2048 + k * 1024); } while (0)
; #define G_MMA(ai, bj, At, Bt) do { __builtin_amdgcn_s_setprio(1); _Pragma("unroll") for (int m = 0; m < 4; ++m) _Pragma("unroll") for (int n = 0; n < 2; ++n) _Pragma("unroll") for (int k = 0; k < 2; ++k) \
;         acc[ai][bj][m][n] = __builtin_amdgcn_mfma_f32_16x16x32_bf16(Bt[n][k], At[m][k], acc[ai][bj][m][n], 0, 0, 0); __builtin_amdgcn_s_setprio(0); } while (0)
; #define G_WAIT_L(n) asm volatile("s_waitcnt lgkmcnt(" #n ")" ::: "memory")
; #define G_BAR __builtin_amdgcn_s_barrier()
; #define G_SCHED __builtin_amdgcn_sched_barrier(0)
; template <class J>
; DI void gemm_phase(LAS unsigned char* lds, const J& job) {
;     ...
;     for (int t = 0; t < nt; t += 2) {
;       const bool last = (t == nt - 2);
;       const char* a1 = cA + G_KT(t + 1);
;       const char* a2 = last ? nA + G_KT(0) : cA + G_KT(t + 2); const char* b2 = last ? nB + G_KT(0) : cB + G_KT(t + 2);
;       const char* a3 = last ? nA + G_KT(1) : cA + G_KT(t + 3); const char* b3 = last ? nB + G_KT(1) : cB + G_KT(t + 3);
;       G_LDB(B0, 0, 0); G_SCHED; G_LDA(At, 0, 0); G_STAGE(G_SA(1, 1), a1 + hstepA, voffA);
;       G_WAIT_L(8); G_BAR; G_WAIT_L(0); G_MMA(0, 0, At, B0); G_BAR; G_SCHED;
;       G_LDB(B1, 0, 1); G_STAGE(G_SB(0, 0), b2, voffB);
;       G_BAR; G_WAIT_L(0); G_MMA(0, 1, At, B1); G_BAR;
;       G_LDA(At, 0, 1); G_STAGE(G_SA(0, 0), a2, voffA);
;       G_BAR; G_WAIT_L(0); G_MMA(1, 0, At, B0); G_BAR; G_SCHED;
.LBB0_104:
	s_add_i32 s1, s56, 0xffffff80
	s_and_b32 s0, s7, 0x380
	s_and_b32 s1, s1, 0x380
	s_add_u32 s57, s64, s1
	s_addc_u32 s66, s65, 0
	s_add_u32 s1, s62, s1
	s_addc_u32 s67, s63, 0
	s_and_b32 s68, s56, 0x380
	s_add_u32 s80, s64, s68
	s_addc_u32 s69, s65, 0
	s_add_u32 s97, s62, s68
	s_addc_u32 vcc_lo, s63, 0
	s_cmp_eq_u32 s6, 4
	s_cselect_b32 s71, s83, s66
	s_cselect_b32 s70, s47, s57
	s_cselect_b32 s73, s87, s67
	s_cselect_b32 s72, s86, s1
	s_cselect_b32 s69, s94, s69
	s_cselect_b32 s68, s33, s80
	s_cselect_b32 s67, s5, vcc_lo
	s_cselect_b32 s66, s96, s97
	s_add_i32 s1, s84, 0x100
	v_add_u32_e32 v134, s1, v138
	ds_read_b128 v[140:143], v134
	ds_read_b128 v[148:151], v134 offset:1024
	ds_read_b128 v[152:155], v134 offset:2048
	ds_read_b128 v[156:159], v134 offset:3072
	s_add_u32 vcc_lo, s9, s0
	s_addc_u32 vcc_hi, s17, 0
	v_lshl_add_u64 v[134:135], vcc, 0, v[132:133]
	s_add_i32 m0, s25, 0xc000
	ds_read_b128 v[160:163], v139
	ds_read_b128 v[164:167], v139 offset:1024
	ds_read_b128 v[168:171], v139 offset:2048
	ds_read_b128 v[172:175], v139 offset:3072
	ds_read_b128 v[176:179], v139 offset:4096
	ds_read_b128 v[180:183], v139 offset:5120
	ds_read_b128 v[184:187], v139 offset:6144
	ds_read_b128 v[188:191], v139 offset:7168
	global_load_lds_dwordx4 v[134:135], off
	v_lshl_add_u64 v[134:135], vcc, 0, v[130:131]
	s_add_i32 m0, s25, 0xe000
	s_nop 0
	global_load_lds_dwordx4 v[134:135], off
	s_waitcnt lgkmcnt(8)
	s_barrier
	s_waitcnt lgkmcnt(0)
	v_mfma_f32_16x16x32_bf16 v[124:127], v[140:143], v[160:163], v[124:127]
	v_mfma_f32_16x16x32_bf16 v[120:123], v[152:155], v[160:163], v[120:123]
	v_mfma_f32_16x16x32_bf16 v[116:119], v[140:143], v[168:171], v[116:119]
	v_mfma_f32_16x16x32_bf16 v[108:111], v[152:155], v[168:171], v[108:111]
	v_mfma_f32_16x16x32_bf16 v[100:103], v[140:143], v[176:179], v[100:103]
	v_mfma_f32_16x16x32_bf16 v[92:95], v[152:155], v[176:179], v[92:95]
	v_mfma_f32_16x16x32_bf16 v[84:87], v[140:143], v[184:187], v[84:87]
	v_mfma_f32_16x16x32_bf16 v[76:79], v[152:155], v[184:187], v[76:79]
	v_mfma_f32_16x16x32_bf16 v[124:127], v[148:151], v[164:167], v[124:127]
	v_mfma_f32_16x16x32_bf16 v[120:123], v[156:159], v[164:167], v[120:123]
	v_mfma_f32_16x16x32_bf16 v[116:119], v[148:151], v[172:175], v[116:119]
	v_mfma_f32_16x16x32_bf16 v[108:111], v[156:159], v[172:175], v[108:111]
	v_mfma_f32_16x16x32_bf16 v[100:103], v[148:151], v[180:183], v[100:103]
	v_mfma_f32_16x16x32_bf16 v[92:95], v[156:159], v[180:183], v[92:95]
	v_mfma_f32_16x16x32_bf16 v[84:87], v[148:151], v[188:191], v[84:87]
	v_mfma_f32_16x16x32_bf16 v[76:79], v[156:159], v[188:191], v[76:79]
	s_barrier
	s_add_i32 s0, s85, 0x100
	v_add_u32_e32 v134, s0, v138
	s_add_i32 s1, s1, s24
	ds_read_b128 v[192:195], v134
	ds_read_b128 v[196:199], v134 offset:1024
	ds_read_b128 v[200:203], v134 offset:2048
	ds_read_b128 v[204:207], v134 offset:3072
	v_lshl_add_u64 v[134:135], s[72:73], 0, v[146:147]
	s_mov_b32 m0, s1
	s_nop 0
	global_load_lds_dwordx4 v[134:135], off
	v_lshl_add_u64 v[134:135], s[72:73], 0, v[128:129]
	s_add_i32 m0, s1, 0x2000
	s_nop 0
	global_load_lds_dwordx4 v[134:135], off
	s_barrier
	s_waitcnt lgkmcnt(0)
	v_mfma_f32_16x16x32_bf16 v[112:115], v[192:195], v[160:163], v[112:115]
	v_mfma_f32_16x16x32_bf16 v[104:107], v[200:203], v[160:163], v[104:107]
	v_mfma_f32_16x16x32_bf16 v[96:99], v[192:195], v[168:171], v[96:99]
	v_mfma_f32_16x16x32_bf16 v[88:91], v[200:203], v[168:171], v[88:91]
	v_mfma_f32_16x16x32_bf16 v[80:83], v[192:195], v[176:179], v[80:83]
	v_mfma_f32_16x16x32_bf16 v[72:75], v[200:203], v[176:179], v[72:75]
	v_mfma_f32_16x16x32_bf16 v[68:71], v[192:195], v[184:187], v[68:71]
	v_mfma_f32_16x16x32_bf16 v[64:67], v[200:203], v[184:187], v[64:67]
	v_mfma_f32_16x16x32_bf16 v[112:115], v[196:199], v[164:167], v[112:115]
	v_mfma_f32_16x16x32_bf16 v[104:107], v[204:207], v[164:167], v[104:107]
	v_mfma_f32_16x16x32_bf16 v[96:99], v[196:199], v[172:175], v[96:99]
	v_mfma_f32_16x16x32_bf16 v[88:91], v[204:207], v[172:175], v[88:91]
	v_mfma_f32_16x16x32_bf16 v[80:83], v[196:199], v[180:183], v[80:83]
	v_mfma_f32_16x16x32_bf16 v[72:75], v[204:207], v[180:183], v[72:75]
	v_mfma_f32_16x16x32_bf16 v[68:71], v[196:199], v[188:191], v[68:71]
	v_mfma_f32_16x16x32_bf16 v[64:67], v[204:207], v[188:191], v[64:67]
	s_barrier
	s_mov_b32 m0, s25
	v_lshl_add_u64 v[134:135], s[70:71], 0, v[132:133]
	ds_read_b128 v[160:163], v139 offset:16384
	ds_read_b128 v[164:167], v139 offset:17408
	ds_read_b128 v[168:171], v139 offset:18432
	ds_read_b128 v[172:175], v139 offset:19456
	ds_read_b128 v[176:179], v139 offset:20480
	ds_read_b128 v[180:183], v139 offset:21504
	ds_read_b128 v[184:187], v139 offset:22528
	ds_read_b128 v[188:191], v139 offset:23552
	global_load_lds_dwordx4 v[134:135], off
	v_lshl_add_u64 v[134:135], s[70:71], 0, v[130:131]
	s_mov_b32 m0, s36
	s_nop 0
	global_load_lds_dwordx4 v[134:135], off
	s_barrier
	s_waitcnt lgkmcnt(0)
	v_mfma_f32_16x16x32_bf16 v[60:63], v[140:143], v[160:163], v[60:63]
	v_mfma_f32_16x16x32_bf16 v[56:59], v[152:155], v[160:163], v[56:59]
	v_mfma_f32_16x16x32_bf16 v[52:55], v[140:143], v[168:171], v[52:55]
	v_mfma_f32_16x16x32_bf16 v[44:47], v[152:155], v[168:171], v[44:47]
	v_mfma_f32_16x16x32_bf16 v[36:39], v[140:143], v[176:179], v[36:39]
	v_mfma_f32_16x16x32_bf16 v[28:31], v[152:155], v[176:179], v[28:31]
	v_mfma_f32_16x16x32_bf16 v[20:23], v[140:143], v[184:187], v[20:23]
	v_mfma_f32_16x16x32_bf16 v[12:15], v[152:155], v[184:187], v[12:15]
	v_mfma_f32_16x16x32_bf16 v[60:63], v[148:151], v[164:167], v[60:63]
	v_mfma_f32_16x16x32_bf16 v[56:59], v[156:159], v[164:167], v[56:59]
	v_mfma_f32_16x16x32_bf16 v[52:55], v[148:151], v[172:175], v[52:55]
	v_mfma_f32_16x16x32_bf16 v[44:47], v[156:159], v[172:175], v[44:47]
	v_mfma_f32_16x16x32_bf16 v[36:39], v[148:151], v[180:183], v[36:39]
	v_mfma_f32_16x16x32_bf16 v[28:31], v[156:159], v[180:183], v[28:31]
	v_mfma_f32_16x16x32_bf16 v[20:23], v[148:151], v[188:191], v[20:23]
	v_mfma_f32_16x16x32_bf16 v[12:15], v[156:159], v[188:191], v[12:15]
	s_barrier
; #define G_STAGE(bufoff, gbase, voff) do { _Pragma("unroll") for (int _i = 0; _i < 2; ++_i) \
;         __builtin_amdgcn_global_load_lds((const unsigned*)((const char*)(gbase) + (voff)[_i]), (LAS unsigned*)(lds + (bufoff) + ldsw + _i * 8192), 16, 0, 0); } while (0)
; #define G_LDA(dst, b, h) do { _Pragma("unroll") for (int m = 0; m < 4; ++m) _Pragma("unroll") for (int k = 0; k < 2; ++k) dst[m][k] = *(const LAS bf16x8*)(lds + G_SA(b, h) + aoff + m * 2048 + k * 1024); } while (0)
; #define G_LDB(dst, b, h) do { _Pragma("unroll") for (int n = 0; n < 2; ++n) _Pragma("unroll") for (int k = 0; k < 2; ++k) dst[n][k] = *(const LAS bf16x8*)(lds + G_SB(b, h) + boff + n * 2048 + k * 1024); } while (0)
; #define G_MMA(ai, bj, At, Bt) do { __builtin_amdgcn_s_setprio(1); _Pragma("unroll") for (int m = 0; m < 4; ++m) _Pragma("unroll") for (int n = 0; n < 2; ++n) _Pragma("unroll") for (int k = 0; k < 2; ++k) \
;         acc[ai][bj][m][n] = __builtin_amdgcn_mfma_f32_16x16x32_bf16(Bt[n][k], At[m][k], acc[ai][bj][m][n], 0, 0, 0); __builtin_amdgcn_s_setprio(0); } while (0)
; #define G_WAIT_V(n) asm volatile("s_waitcnt vmcnt(" #n ")" ::: "memory")
; #define G_WAIT_L(n) asm volatile("s_waitcnt lgkmcnt(" #n ")" ::: "memory")
; #define G_BAR __builtin_amdgcn_s_barrier()
; #define G_SCHED __builtin_amdgcn_sched_barrier(0)
; template <class J>
; DI void gemm_phase(LAS unsigned char* lds, const J& job) {
;     ...
;       G_STAGE(G_SB(0, 1), b2 + hstepB, voffB);
;       G_WAIT_V(6); G_BAR; G_MMA(1, 1, At, B1); G_BAR;
;       G_LDB(B0, 1, 0); G_SCHED; G_LDA(At, 1, 0); G_STAGE(G_SA(0, 1), a2 + hstepA, voffA);
;       G_WAIT_L(8); G_BAR; G_WAIT_L(0); G_MMA(0, 0, At, B0); G_BAR; G_SCHED;
;       G_LDB(B1, 1, 1); G_STAGE(G_SB(1, 0), b3, voffB);
;       G_BAR; G_WAIT_L(0); G_MMA(0, 1, At, B1); G_BAR;
;       G_LDA(At, 1, 1); G_STAGE(G_SA(1, 0), a3, voffA);
	s_add_u32 s72, s72, 0x20000
	s_addc_u32 s73, s73, 0
	s_add_i32 s0, s0, s24
	v_lshl_add_u64 v[134:135], s[72:73], 0, v[146:147]
	s_mov_b32 m0, s0
	s_nop 0
	global_load_lds_dwordx4 v[134:135], off
	v_lshl_add_u64 v[134:135], s[72:73], 0, v[128:129]
	s_add_i32 m0, s0, 0x2000
	s_nop 0
	global_load_lds_dwordx4 v[134:135], off
	s_waitcnt vmcnt(6)
	s_barrier
	v_mfma_f32_16x16x32_bf16 v[48:51], v[192:195], v[160:163], v[48:51]
	v_mfma_f32_16x16x32_bf16 v[40:43], v[200:203], v[160:163], v[40:43]
	v_mfma_f32_16x16x32_bf16 v[32:35], v[192:195], v[168:171], v[32:35]
	v_mfma_f32_16x16x32_bf16 v[24:27], v[200:203], v[168:171], v[24:27]
	v_mfma_f32_16x16x32_bf16 v[16:19], v[192:195], v[176:179], v[16:19]
	v_mfma_f32_16x16x32_bf16 v[8:11], v[200:203], v[176:179], v[8:11]
	v_mfma_f32_16x16x32_bf16 v[4:7], v[192:195], v[184:187], v[4:7]
	v_mfma_f32_16x16x32_bf16 v[0:3], v[200:203], v[184:187], v[0:3]
	v_mfma_f32_16x16x32_bf16 v[48:51], v[196:199], v[164:167], v[48:51]
	v_mfma_f32_16x16x32_bf16 v[40:43], v[204:207], v[164:167], v[40:43]
	v_mfma_f32_16x16x32_bf16 v[32:35], v[196:199], v[172:175], v[32:35]
	v_mfma_f32_16x16x32_bf16 v[24:27], v[204:207], v[172:175], v[24:27]
	v_mfma_f32_16x16x32_bf16 v[16:19], v[196:199], v[180:183], v[16:19]
	v_mfma_f32_16x16x32_bf16 v[8:11], v[204:207], v[180:183], v[8:11]
	v_mfma_f32_16x16x32_bf16 v[4:7], v[196:199], v[188:191], v[4:7]
	v_mfma_f32_16x16x32_bf16 v[0:3], v[204:207], v[188:191], v[0:3]
	s_barrier
	s_add_i32 s0, s88, 0x100
	v_add_u32_e32 v134, s0, v138
	ds_read_b128 v[140:143], v134
	ds_read_b128 v[148:151], v134 offset:1024
	ds_read_b128 v[152:155], v134 offset:2048
	ds_read_b128 v[156:159], v134 offset:3072
	s_add_u32 s70, s70, 0x80000
	s_addc_u32 s71, s71, 0
	s_mov_b32 m0, s37
	v_lshl_add_u64 v[134:135], s[70:71], 0, v[132:133]
	ds_read_b128 v[160:163], v139 offset:32768
	ds_read_b128 v[164:167], v139 offset:33792
	ds_read_b128 v[168:171], v139 offset:34816
	ds_read_b128 v[172:175], v139 offset:35840
	ds_read_b128 v[176:179], v139 offset:36864
	ds_read_b128 v[180:183], v139 offset:37888
	ds_read_b128 v[184:187], v139 offset:38912
	ds_read_b128 v[188:191], v139 offset:39936
	global_load_lds_dwordx4 v[134:135], off
	v_lshl_add_u64 v[134:135], s[70:71], 0, v[130:131]
	s_mov_b32 m0, s38
	s_nop 0
	global_load_lds_dwordx4 v[134:135], off
	s_waitcnt lgkmcnt(8)
	s_barrier
	s_waitcnt lgkmcnt(0)
	v_mfma_f32_16x16x32_bf16 v[124:127], v[140:143], v[160:163], v[124:127]
	v_mfma_f32_16x16x32_bf16 v[120:123], v[152:155], v[160:163], v[120:123]
	v_mfma_f32_16x16x32_bf16 v[116:119], v[140:143], v[168:171], v[116:119]
	v_mfma_f32_16x16x32_bf16 v[108:111], v[152:155], v[168:171], v[108:111]
	v_mfma_f32_16x16x32_bf16 v[100:103], v[140:143], v[176:179], v[100:103]
	v_mfma_f32_16x16x32_bf16 v[92:95], v[152:155], v[176:179], v[92:95]
	v_mfma_f32_16x16x32_bf16 v[84:87], v[140:143], v[184:187], v[84:87]
	v_mfma_f32_16x16x32_bf16 v[76:79], v[152:155], v[184:187], v[76:79]
	v_mfma_f32_16x16x32_bf16 v[124:127], v[148:151], v[164:167], v[124:127]
	v_mfma_f32_16x16x32_bf16 v[120:123], v[156:159], v[164:167], v[120:123]
	v_mfma_f32_16x16x32_bf16 v[116:119], v[148:151], v[172:175], v[116:119]
	v_mfma_f32_16x16x32_bf16 v[108:111], v[156:159], v[172:175], v[108:111]
	v_mfma_f32_16x16x32_bf16 v[100:103], v[148:151], v[180:183], v[100:103]
	v_mfma_f32_16x16x32_bf16 v[92:95], v[156:159], v[180:183], v[92:95]
	v_mfma_f32_16x16x32_bf16 v[84:87], v[148:151], v[188:191], v[84:87]
	v_mfma_f32_16x16x32_bf16 v[76:79], v[156:159], v[188:191], v[76:79]
	s_barrier
	s_add_i32 s1, s89, 0x100
	v_add_u32_e32 v134, s1, v138
	s_add_i32 s0, s0, s24
	ds_read_b128 v[192:195], v134
	ds_read_b128 v[196:199], v134 offset:1024
	ds_read_b128 v[200:203], v134 offset:2048
	ds_read_b128 v[204:207], v134 offset:3072
	v_lshl_add_u64 v[134:135], s[66:67], 0, v[146:147]
	s_mov_b32 m0, s0
	s_nop 0
	global_load_lds_dwordx4 v[134:135], off
	v_lshl_add_u64 v[134:135], s[66:67], 0, v[128:129]
	s_add_i32 m0, s0, 0x2000
	s_nop 0
	global_load_lds_dwordx4 v[134:135], off
	s_barrier
	s_waitcnt lgkmcnt(0)
	v_mfma_f32_16x16x32_bf16 v[112:115], v[192:195], v[160:163], v[112:115]
	v_mfma_f32_16x16x32_bf16 v[104:107], v[200:203], v[160:163], v[104:107]
	v_mfma_f32_16x16x32_bf16 v[96:99], v[192:195], v[168:171], v[96:99]
	v_mfma_f32_16x16x32_bf16 v[88:91], v[200:203], v[168:171], v[88:91]
	v_mfma_f32_16x16x32_bf16 v[80:83], v[192:195], v[176:179], v[80:83]
	v_mfma_f32_16x16x32_bf16 v[72:75], v[200:203], v[176:179], v[72:75]
	v_mfma_f32_16x16x32_bf16 v[68:71], v[192:195], v[184:187], v[68:71]
	v_mfma_f32_16x16x32_bf16 v[64:67], v[200:203], v[184:187], v[64:67]
	v_mfma_f32_16x16x32_bf16 v[112:115], v[196:199], v[164:167], v[112:115]
	v_mfma_f32_16x16x32_bf16 v[104:107], v[204:207], v[164:167], v[104:107]
	v_mfma_f32_16x16x32_bf16 v[96:99], v[196:199], v[172:175], v[96:99]
	v_mfma_f32_16x16x32_bf16 v[88:91], v[204:207], v[172:175], v[88:91]
	v_mfma_f32_16x16x32_bf16 v[80:83], v[196:199], v[180:183], v[80:83]
	v_mfma_f32_16x16x32_bf16 v[72:75], v[204:207], v[180:183], v[72:75]
	v_mfma_f32_16x16x32_bf16 v[68:71], v[196:199], v[188:191], v[68:71]
	v_mfma_f32_16x16x32_bf16 v[64:67], v[204:207], v[188:191], v[64:67]
	s_barrier
	s_mov_b32 m0, s75
	v_lshl_add_u64 v[134:135], s[68:69], 0, v[132:133]
	ds_read_b128 v[160:163], v139 offset:49152
	ds_read_b128 v[164:167], v139 offset:50176
	ds_read_b128 v[168:171], v139 offset:51200
	ds_read_b128 v[172:175], v139 offset:52224
	ds_read_b128 v[176:179], v139 offset:53248
	ds_read_b128 v[180:183], v139 offset:54272
	ds_read_b128 v[184:187], v139 offset:55296
	ds_read_b128 v[188:191], v139 offset:56320
	global_load_lds_dwordx4 v[134:135], off
	v_lshl_add_u64 v[134:135], s[68:69], 0, v[130:131]
	s_mov_b32 m0, s76
	s_nop 0
	global_load_lds_dwordx4 v[134:135], off
	s_barrier
; #define G_STAGE(bufoff, gbase, voff) do { _Pragma("unroll") for (int _i = 0; _i < 2; ++_i) \
;         __builtin_amdgcn_global_load_lds((const unsigned*)((const char*)(gbase) + (voff)[_i]), (LAS unsigned*)(lds + (bufoff) + ldsw + _i * 8192), 16, 0, 0); } while (0)
; #define G_MMA(ai, bj, At, Bt) do { __builtin_amdgcn_s_setprio(1); _Pragma("unroll") for (int m = 0; m < 4; ++m) _Pragma("unroll") for (int n = 0; n < 2; ++n) _Pragma("unroll") for (int k = 0; k < 2; ++k) \
;         acc[ai][bj][m][n] = __builtin_amdgcn_mfma_f32_16x16x32_bf16(Bt[n][k], At[m][k], acc[ai][bj][m][n], 0, 0, 0); __builtin_amdgcn_s_setprio(0); } while (0)
; #define G_WAIT_V(n) asm volatile("s_waitcnt vmcnt(" #n ")" ::: "memory")
; #define G_WAIT_L(n) asm volatile("s_waitcnt lgkmcnt(" #n ")" ::: "memory")
; #define G_BAR __builtin_amdgcn_s_barrier()
; #define G_SCHED __builtin_amdgcn_sched_barrier(0)
; template <class J>
; DI void gemm_phase(LAS unsigned char* lds, const J& job) {
;     ...
;       G_BAR; G_WAIT_L(0); G_MMA(1, 0, At, B0); G_BAR; G_SCHED;
;       G_STAGE(G_SB(1, 1), b3 + hstepB, voffB);
;       G_WAIT_V(6); G_BAR; G_MMA(1, 1, At, B1); G_BAR;
	s_waitcnt lgkmcnt(0)
	v_mfma_f32_16x16x32_bf16 v[60:63], v[140:143], v[160:163], v[60:63]
	v_mfma_f32_16x16x32_bf16 v[56:59], v[152:155], v[160:163], v[56:59]
	v_mfma_f32_16x16x32_bf16 v[52:55], v[140:143], v[168:171], v[52:55]
	v_mfma_f32_16x16x32_bf16 v[44:47], v[152:155], v[168:171], v[44:47]
	v_mfma_f32_16x16x32_bf16 v[36:39], v[140:143], v[176:179], v[36:39]
	v_mfma_f32_16x16x32_bf16 v[28:31], v[152:155], v[176:179], v[28:31]
	v_mfma_f32_16x16x32_bf16 v[20:23], v[140:143], v[184:187], v[20:23]
	v_mfma_f32_16x16x32_bf16 v[12:15], v[152:155], v[184:187], v[12:15]
	v_mfma_f32_16x16x32_bf16 v[60:63], v[148:151], v[164:167], v[60:63]
	v_mfma_f32_16x16x32_bf16 v[56:59], v[156:159], v[164:167], v[56:59]
	v_mfma_f32_16x16x32_bf16 v[52:55], v[148:151], v[172:175], v[52:55]
	v_mfma_f32_16x16x32_bf16 v[44:47], v[156:159], v[172:175], v[44:47]
	v_mfma_f32_16x16x32_bf16 v[36:39], v[148:151], v[180:183], v[36:39]
	v_mfma_f32_16x16x32_bf16 v[28:31], v[156:159], v[180:183], v[28:31]
	v_mfma_f32_16x16x32_bf16 v[20:23], v[148:151], v[188:191], v[20:23]
	v_mfma_f32_16x16x32_bf16 v[12:15], v[156:159], v[188:191], v[12:15]
	s_barrier
	s_add_u32 s66, s66, 0x20000
	s_addc_u32 s67, s67, 0
	s_add_i32 s0, s1, s24
	v_lshl_add_u64 v[134:135], s[66:67], 0, v[146:147]
	s_mov_b32 m0, s0
	s_nop 0
	global_load_lds_dwordx4 v[134:135], off
	v_lshl_add_u64 v[134:135], s[66:67], 0, v[128:129]
	s_add_i32 m0, s0, 0x2000
	s_nop 0
	global_load_lds_dwordx4 v[134:135], off
	s_waitcnt vmcnt(6)
	s_barrier
	v_mfma_f32_16x16x32_bf16 v[48:51], v[192:195], v[160:163], v[48:51]
	v_mfma_f32_16x16x32_bf16 v[40:43], v[200:203], v[160:163], v[40:43]
	v_mfma_f32_16x16x32_bf16 v[32:35], v[192:195], v[168:171], v[32:35]
	v_mfma_f32_16x16x32_bf16 v[24:27], v[200:203], v[168:171], v[24:27]
	v_mfma_f32_16x16x32_bf16 v[16:19], v[192:195], v[176:179], v[16:19]
	v_mfma_f32_16x16x32_bf16 v[8:11], v[200:203], v[176:179], v[8:11]
	v_mfma_f32_16x16x32_bf16 v[4:7], v[192:195], v[184:187], v[4:7]
	v_mfma_f32_16x16x32_bf16 v[0:3], v[200:203], v[184:187], v[0:3]
	v_mfma_f32_16x16x32_bf16 v[48:51], v[196:199], v[164:167], v[48:51]
	v_mfma_f32_16x16x32_bf16 v[40:43], v[204:207], v[164:167], v[40:43]
	v_mfma_f32_16x16x32_bf16 v[32:35], v[196:199], v[172:175], v[32:35]
	v_mfma_f32_16x16x32_bf16 v[24:27], v[204:207], v[172:175], v[24:27]
	v_mfma_f32_16x16x32_bf16 v[16:19], v[196:199], v[180:183], v[16:19]
	v_mfma_f32_16x16x32_bf16 v[8:11], v[204:207], v[180:183], v[8:11]
	v_mfma_f32_16x16x32_bf16 v[4:7], v[196:199], v[188:191], v[4:7]
	v_mfma_f32_16x16x32_bf16 v[0:3], v[204:207], v[188:191], v[0:3]
	s_add_i32 s6, s6, 2
	s_addk_i32 s56, 0x100
	s_addk_i32 s7, 0x100
	s_cmp_gt_u32 s6, 5
	s_barrier
	s_cbranch_scc0 .LBB0_104
; DI unsigned pk2(float lo, float hi) { unsigned r; asm("v_cvt_pk_bf16_f32 %0, %1, %2" : "=v"(r) : "v"(lo), "v"(hi)); return r; }
;   DI void epi(const Acc& acc, const Unit& u, int wr, int wc, int fr, int fq) const {
; #pragma unroll
;     for (int ai = 0; ai < 2; ++ai)
; #pragma unroll
;       for (int m = 0; m < 4; ++m) {
;         const int row = u.pm * 256 + ai * HALF + wr * 64 + m * 16 + fr;
; #pragma unroll
;         for (int bj = 0; bj < 2; ++bj) {
;           const int col = u.pn * 256 + bj * HALF + wc * 32 + 8 * fq;
;           const f32x4 v0 = acc[ai][bj][m][0], v1 = acc[ai][bj][m][1];
;           u32x4 o; o.x = pk2(v0.x, v0.y); o.y = pk2(v0.z, v0.w); o.z = pk2(v1.x, v1.y); o.w = pk2(v1.z, v1.w);
;           *(u32x4*)(Z + (size_t)row * NGATE + col) = o;
;         }
;       }
;   }
	v_mov_b32_e32 v135, v137
	v_mov_b32_e32 v134, v136
	s_lshl_b32 s0, s22, 8
	s_add_i32 s0, s0, s44
	v_add_u32_e32 v134, s0, v134
	s_lshl_b32 s0, s46, 8
	s_or_b32 s0, s0, s45
	v_cvt_pk_bf16_f32 v68, v68, v69
	v_cvt_pk_bf16_f32 v69, v70, v71
	v_cvt_pk_bf16_f32 v70, v64, v65
	v_add_u32_e32 v64, 0x80, v134
	v_lshl_add_u32 v140, v135, 3, s0
	v_ashrrev_i32_e32 v135, 31, v134
	v_ashrrev_i32_e32 v65, 31, v64
	v_lshlrev_b64 v[142:143], 14, v[134:135]
	v_ashrrev_i32_e32 v141, 31, v140
	v_lshlrev_b64 v[64:65], 14, v[64:65]
	v_cvt_pk_bf16_f32 v124, v124, v125
	v_cvt_pk_bf16_f32 v125, v126, v127
	v_cvt_pk_bf16_f32 v126, v120, v121
	v_cvt_pk_bf16_f32 v127, v122, v123
	v_lshl_add_u64 v[122:123], s[26:27], 0, v[142:143]
	v_lshlrev_b64 v[120:121], 1, v[140:141]
	v_cvt_pk_bf16_f32 v112, v112, v113
	v_cvt_pk_bf16_f32 v113, v114, v115
	v_cvt_pk_bf16_f32 v114, v104, v105
	v_add_u32_e32 v104, 16, v134
	v_cvt_pk_bf16_f32 v60, v60, v61
	v_cvt_pk_bf16_f32 v61, v62, v63
	v_cvt_pk_bf16_f32 v62, v56, v57
	v_lshl_add_u64 v[56:57], s[26:27], 0, v[64:65]
	v_cvt_pk_bf16_f32 v48, v48, v49
	v_cvt_pk_bf16_f32 v49, v50, v51
	v_cvt_pk_bf16_f32 v50, v40, v41
	v_add_u32_e32 v40, 0x90, v134
	v_lshl_add_u64 v[122:123], v[122:123], 0, v[120:121]
	v_ashrrev_i32_e32 v105, 31, v104
	v_lshl_add_u64 v[56:57], v[56:57], 0, v[120:121]
	v_ashrrev_i32_e32 v41, 31, v40
	v_cvt_pk_bf16_f32 v115, v106, v107
	global_store_dwordx4 v[122:123], v[112:115], off offset:256
	v_cvt_pk_bf16_f32 v51, v42, v43
	global_store_dwordx4 v[56:57], v[48:51], off offset:256
	v_cvt_pk_bf16_f32 v106, v108, v109
	v_cvt_pk_bf16_f32 v96, v96, v97
	v_cvt_pk_bf16_f32 v97, v98, v99
	s_nop 0
	v_lshlrev_b64 v[112:113], 14, v[104:105]
	v_lshl_add_u64 v[108:109], s[26:27], 0, v[112:113]
	v_lshlrev_b64 v[48:49], 14, v[40:41]
	v_cvt_pk_bf16_f32 v98, v88, v89
	v_add_u32_e32 v88, 32, v134
	v_cvt_pk_bf16_f32 v42, v44, v45
	v_lshl_add_u64 v[44:45], s[26:27], 0, v[48:49]
	v_cvt_pk_bf16_f32 v32, v32, v33
	v_cvt_pk_bf16_f32 v33, v34, v35
	v_cvt_pk_bf16_f32 v34, v24, v25
	v_add_u32_e32 v24, 0xa0, v134
	v_lshl_add_u64 v[108:109], v[108:109], 0, v[120:121]
	v_ashrrev_i32_e32 v89, 31, v88
	v_lshl_add_u64 v[44:45], v[44:45], 0, v[120:121]
	v_ashrrev_i32_e32 v25, 31, v24
	v_cvt_pk_bf16_f32 v99, v90, v91
	global_store_dwordx4 v[108:109], v[96:99], off offset:256
	v_cvt_pk_bf16_f32 v35, v26, v27
	global_store_dwordx4 v[44:45], v[32:35], off offset:256
	v_cvt_pk_bf16_f32 v90, v92, v93
	v_cvt_pk_bf16_f32 v80, v80, v81
	v_cvt_pk_bf16_f32 v81, v82, v83
	s_nop 0
	v_lshlrev_b64 v[96:97], 14, v[88:89]
	v_lshl_add_u64 v[92:93], s[26:27], 0, v[96:97]
	v_lshlrev_b64 v[32:33], 14, v[24:25]
	v_cvt_pk_bf16_f32 v82, v72, v73
	v_add_u32_e32 v72, 48, v134
	v_cvt_pk_bf16_f32 v26, v28, v29
	v_lshl_add_u64 v[28:29], s[26:27], 0, v[32:33]
	v_cvt_pk_bf16_f32 v16, v16, v17
	v_cvt_pk_bf16_f32 v17, v18, v19
	v_cvt_pk_bf16_f32 v18, v8, v9
	v_add_u32_e32 v8, 0xb0, v134
	v_lshl_add_u64 v[92:93], v[92:93], 0, v[120:121]
	v_ashrrev_i32_e32 v73, 31, v72
	v_lshl_add_u64 v[28:29], v[28:29], 0, v[120:121]
	v_ashrrev_i32_e32 v9, 31, v8
	v_cvt_pk_bf16_f32 v83, v74, v75
	global_store_dwordx4 v[92:93], v[80:83], off offset:256
	v_cvt_pk_bf16_f32 v19, v10, v11
	global_store_dwordx4 v[28:29], v[16:19], off offset:256
	v_cvt_pk_bf16_f32 v74, v76, v77
	v_cvt_pk_bf16_f32 v10, v12, v13
	s_and_b64 vcc, exec, s[12:13]
	v_lshlrev_b64 v[80:81], 14, v[72:73]
	v_lshlrev_b64 v[16:17], 14, v[8:9]
	v_lshl_add_u64 v[76:77], s[26:27], 0, v[80:81]
	v_lshl_add_u64 v[12:13], s[26:27], 0, v[16:17]
	v_lshl_add_u64 v[76:77], v[76:77], 0, v[120:121]
	v_lshl_add_u64 v[12:13], v[12:13], 0, v[120:121]
	s_mov_b32 s46, s8
	s_mov_b32 s22, s16
	s_mov_b64 s[62:63], s[20:21]
	s_mov_b64 s[64:65], s[18:19]
	global_store_dwordx4 v[122:123], v[124:127], off
	v_cvt_pk_bf16_f32 v104, v116, v117
	v_cvt_pk_bf16_f32 v105, v118, v119
	v_cvt_pk_bf16_f32 v107, v110, v111
	global_store_dwordx4 v[108:109], v[104:107], off
	v_cvt_pk_bf16_f32 v88, v100, v101
	v_cvt_pk_bf16_f32 v89, v102, v103
	v_cvt_pk_bf16_f32 v91, v94, v95
	global_store_dwordx4 v[92:93], v[88:91], off
	v_cvt_pk_bf16_f32 v72, v84, v85
	v_cvt_pk_bf16_f32 v73, v86, v87
	v_cvt_pk_bf16_f32 v75, v78, v79
	global_store_dwordx4 v[76:77], v[72:75], off
	v_cvt_pk_bf16_f32 v71, v66, v67
	global_store_dwordx4 v[76:77], v[68:71], off offset:256
	v_cvt_pk_bf16_f32 v63, v58, v59
	global_store_dwordx4 v[56:57], v[60:63], off
	v_cvt_pk_bf16_f32 v40, v52, v53
	v_cvt_pk_bf16_f32 v41, v54, v55
	v_cvt_pk_bf16_f32 v43, v46, v47
	global_store_dwordx4 v[44:45], v[40:43], off
	v_cvt_pk_bf16_f32 v24, v36, v37
	v_cvt_pk_bf16_f32 v25, v38, v39
	v_cvt_pk_bf16_f32 v27, v30, v31
	global_store_dwordx4 v[28:29], v[24:27], off
	v_cvt_pk_bf16_f32 v8, v20, v21
	v_cvt_pk_bf16_f32 v9, v22, v23
	v_cvt_pk_bf16_f32 v11, v14, v15
	global_store_dwordx4 v[12:13], v[8:11], off
	v_cvt_pk_bf16_f32 v4, v4, v5
	v_cvt_pk_bf16_f32 v5, v6, v7
	v_cvt_pk_bf16_f32 v6, v0, v1
	v_cvt_pk_bf16_f32 v7, v2, v3
	global_store_dwordx4 v[12:13], v[4:7], off offset:256
	s_cbranch_vccz .LBB0_101
	s_setprio 0
	s_waitcnt vmcnt(0)
	v_readlane_b32 s44, v255, 6
	s_cmpk_gt_u32 s4, 0xff
	v_readlane_b32 s45, v255, 7
	s_cbranch_scc1 .LBB0_108
	s_barrier

; #define G_STAGE(bufoff, gbase, voff) do { _Pragma("unroll") for (int _i = 0; _i < 2; ++_i) \
;         __builtin_amdgcn_global_load_lds((const unsigned*)((const char*)(gbase) + (voff)[_i]), (LAS unsigned*)(lds + (bufoff) + ldsw + _i * 8192), 16, 0, 0); } while (0)
; #define G_LDA(dst, b, h) do { _Pragma("unroll") for (int m = 0; m < 4; ++m) _Pragma("unroll") for (int k = 0; k < 2; ++k) dst[m][k] = *(const LAS bf16x8*)(lds + G_SA(b, h) + aoff + m * 2048 + k * 1024); } while (0)
; #define G_LDB(dst, b, h) do { _Pragma("unroll") for (int n = 0; n < 2; ++n) _Pragma("unroll") for (int k = 0; k < 2; ++k) dst[n][k] = *(const LAS bf16x8*)(lds + G_SB(b, h) + boff + n * 2048 + k * 1024); } while (0)
; #define G_MMA(ai, bj, At, Bt) do { __builtin_amdgcn_s_setprio(1); _Pragma("unroll") for (int m = 0; m < 4; ++m) _Pragma("unroll") for (int n = 0; n < 2; ++n) _Pragma("unroll") for (int k = 0; k < 2; ++k) \
;         acc[ai][bj][m][n] = __builtin_amdgcn_mfma_f32_16x16x32_bf16(Bt[n][k], At[m][k], acc[ai][bj][m][n], 0, 0, 0); __builtin_amdgcn_s_setprio(0); } while (0)
; #define G_WAIT_L(n) asm volatile("s_waitcnt lgkmcnt(" #n ")" ::: "memory")
; #define G_BAR __builtin_amdgcn_s_barrier()
; #define G_SCHED __builtin_amdgcn_sched_barrier(0)
; template <class J>
; DI void gemm_phase(LAS unsigned char* lds, const J& job) {
;     ...
;     for (int t = 0; t < nt; t += 2) {
;       const bool last = (t == nt - 2);
;       const char* a1 = cA + G_KT(t + 1);
;       const char* a2 = last ? nA + G_KT(0) : cA + G_KT(t + 2); const char* b2 = last ? nB + G_KT(0) : cB + G_KT(t + 2);
;       const char* a3 = last ? nA + G_KT(1) : cA + G_KT(t + 3); const char* b3 = last ? nB + G_KT(1) : cB + G_KT(t + 3);
;       G_LDB(B0, 0, 0); G_SCHED; G_LDA(At, 0, 0); G_STAGE(G_SA(1, 1), a1 + hstepA, voffA);
;       G_WAIT_L(8); G_BAR; G_WAIT_L(0); G_MMA(0, 0, At, B0); G_BAR; G_SCHED;
;       G_LDB(B1, 0, 1); G_STAGE(G_SB(0, 0), b2, voffB);
;       G_BAR; G_WAIT_L(0); G_MMA(0, 1, At, B1); G_BAR;
;       G_LDA(At, 0, 1); G_STAGE(G_SA(0, 0), a2, voffA);
;       G_BAR; G_WAIT_L(0); G_MMA(1, 0, At, B0); G_BAR; G_SCHED;
.LBB0_282:
	s_add_i32 s1, s56, 0xffffff80
	s_and_b32 s0, s7, 0xf80
	s_and_b32 s1, s1, 0xf00
	s_add_u32 s10, s68, s1
	s_addc_u32 s11, s69, 0
	s_add_u32 s1, s66, s1
	s_addc_u32 s57, s67, 0
	s_and_b32 s70, s56, 0xf80
	s_add_u32 s71, s68, s70
	s_addc_u32 s72, s69, 0
	s_add_u32 s70, s66, s70
	s_addc_u32 s80, s67, 0
	s_cmp_eq_u32 s6, 28
	s_cselect_b32 s75, s46, s11
	s_cselect_b32 s74, s21, s10
	s_cselect_b32 s77, s96, s57
	s_cselect_b32 s76, s47, s1
	s_cselect_b32 s73, s97, s72
	s_cselect_b32 s72, s33, s71
	s_cselect_b32 s71, vcc_hi, s80
	s_cselect_b32 s70, vcc_lo, s70
	s_add_i32 s1, s84, 0x100
	v_add_u32_e32 v142, s1, v150
	ds_read_b128 v[134:137], v142
	ds_read_b128 v[138:141], v142 offset:1024
	ds_read_b128 v[152:155], v142 offset:2048
	ds_read_b128 v[156:159], v142 offset:3072
	s_add_u32 s10, s9, s0
	s_addc_u32 s11, s19, 0
	v_lshl_add_u64 v[142:143], s[10:11], 0, v[128:129]
	s_add_i32 m0, s15, 0xc000
	ds_read_b128 v[160:163], v151
	ds_read_b128 v[164:167], v151 offset:1024
	ds_read_b128 v[168:171], v151 offset:2048
	ds_read_b128 v[172:175], v151 offset:3072
	ds_read_b128 v[176:179], v151 offset:4096
	ds_read_b128 v[180:183], v151 offset:5120
	ds_read_b128 v[184:187], v151 offset:6144
	ds_read_b128 v[188:191], v151 offset:7168
	global_load_lds_dwordx4 v[142:143], off
	v_lshl_add_u64 v[142:143], s[10:11], 0, v[130:131]
	s_add_i32 m0, s15, 0xe000
	s_nop 0
	global_load_lds_dwordx4 v[142:143], off
	s_waitcnt lgkmcnt(8)
	s_barrier
	s_waitcnt lgkmcnt(0)
	v_mfma_f32_16x16x32_bf16 v[124:127], v[134:137], v[160:163], v[124:127]
	v_mfma_f32_16x16x32_bf16 v[120:123], v[152:155], v[160:163], v[120:123]
	v_mfma_f32_16x16x32_bf16 v[108:111], v[134:137], v[168:171], v[108:111]
	v_mfma_f32_16x16x32_bf16 v[104:107], v[152:155], v[168:171], v[104:107]
	v_mfma_f32_16x16x32_bf16 v[92:95], v[134:137], v[176:179], v[92:95]
	v_mfma_f32_16x16x32_bf16 v[88:91], v[152:155], v[176:179], v[88:91]
	v_mfma_f32_16x16x32_bf16 v[76:79], v[134:137], v[184:187], v[76:79]
	v_mfma_f32_16x16x32_bf16 v[72:75], v[152:155], v[184:187], v[72:75]
	v_mfma_f32_16x16x32_bf16 v[124:127], v[138:141], v[164:167], v[124:127]
	v_mfma_f32_16x16x32_bf16 v[120:123], v[156:159], v[164:167], v[120:123]
	v_mfma_f32_16x16x32_bf16 v[108:111], v[138:141], v[172:175], v[108:111]
	v_mfma_f32_16x16x32_bf16 v[104:107], v[156:159], v[172:175], v[104:107]
	v_mfma_f32_16x16x32_bf16 v[92:95], v[138:141], v[180:183], v[92:95]
	v_mfma_f32_16x16x32_bf16 v[88:91], v[156:159], v[180:183], v[88:91]
	v_mfma_f32_16x16x32_bf16 v[76:79], v[138:141], v[188:191], v[76:79]
	v_mfma_f32_16x16x32_bf16 v[72:75], v[156:159], v[188:191], v[72:75]
	s_barrier
	s_add_i32 s0, s85, 0x100
	v_add_u32_e32 v142, s0, v150
	s_add_i32 s1, s1, s5
	ds_read_b128 v[192:195], v142
	ds_read_b128 v[196:199], v142 offset:1024
	ds_read_b128 v[200:203], v142 offset:2048
	ds_read_b128 v[204:207], v142 offset:3072
	v_lshl_add_u64 v[142:143], s[76:77], 0, v[146:147]
	s_mov_b32 m0, s1
	s_nop 0
	global_load_lds_dwordx4 v[142:143], off
	v_lshl_add_u64 v[142:143], s[76:77], 0, v[132:133]
	s_add_i32 m0, s1, 0x2000
	s_nop 0
	global_load_lds_dwordx4 v[142:143], off
	s_barrier
	s_waitcnt lgkmcnt(0)
	v_mfma_f32_16x16x32_bf16 v[116:119], v[192:195], v[160:163], v[116:119]
	v_mfma_f32_16x16x32_bf16 v[112:115], v[200:203], v[160:163], v[112:115]
	v_mfma_f32_16x16x32_bf16 v[100:103], v[192:195], v[168:171], v[100:103]
	v_mfma_f32_16x16x32_bf16 v[96:99], v[200:203], v[168:171], v[96:99]
	v_mfma_f32_16x16x32_bf16 v[84:87], v[192:195], v[176:179], v[84:87]
	v_mfma_f32_16x16x32_bf16 v[80:83], v[200:203], v[176:179], v[80:83]
	v_mfma_f32_16x16x32_bf16 v[68:71], v[192:195], v[184:187], v[68:71]
	v_mfma_f32_16x16x32_bf16 v[64:67], v[200:203], v[184:187], v[64:67]
	v_mfma_f32_16x16x32_bf16 v[116:119], v[196:199], v[164:167], v[116:119]
	v_mfma_f32_16x16x32_bf16 v[112:115], v[204:207], v[164:167], v[112:115]
	v_mfma_f32_16x16x32_bf16 v[100:103], v[196:199], v[172:175], v[100:103]
	v_mfma_f32_16x16x32_bf16 v[96:99], v[204:207], v[172:175], v[96:99]
	v_mfma_f32_16x16x32_bf16 v[84:87], v[196:199], v[180:183], v[84:87]
	v_mfma_f32_16x16x32_bf16 v[80:83], v[204:207], v[180:183], v[80:83]
	v_mfma_f32_16x16x32_bf16 v[68:71], v[196:199], v[188:191], v[68:71]
	v_mfma_f32_16x16x32_bf16 v[64:67], v[204:207], v[188:191], v[64:67]
	s_barrier
	s_mov_b32 m0, s15
	v_lshl_add_u64 v[142:143], s[74:75], 0, v[128:129]
	ds_read_b128 v[160:163], v151 offset:16384
	ds_read_b128 v[164:167], v151 offset:17408
	ds_read_b128 v[168:171], v151 offset:18432
	ds_read_b128 v[172:175], v151 offset:19456
	ds_read_b128 v[176:179], v151 offset:20480
	ds_read_b128 v[180:183], v151 offset:21504
	ds_read_b128 v[184:187], v151 offset:22528
	ds_read_b128 v[188:191], v151 offset:23552
	global_load_lds_dwordx4 v[142:143], off
	v_lshl_add_u64 v[142:143], s[74:75], 0, v[130:131]
	s_mov_b32 m0, s24
	s_nop 0
	global_load_lds_dwordx4 v[142:143], off
	s_barrier
	s_waitcnt lgkmcnt(0)
	v_mfma_f32_16x16x32_bf16 v[60:63], v[134:137], v[160:163], v[60:63]
	v_mfma_f32_16x16x32_bf16 v[56:59], v[152:155], v[160:163], v[56:59]
	v_mfma_f32_16x16x32_bf16 v[44:47], v[134:137], v[168:171], v[44:47]
	v_mfma_f32_16x16x32_bf16 v[40:43], v[152:155], v[168:171], v[40:43]
	v_mfma_f32_16x16x32_bf16 v[28:31], v[134:137], v[176:179], v[28:31]
	v_mfma_f32_16x16x32_bf16 v[24:27], v[152:155], v[176:179], v[24:27]
	v_mfma_f32_16x16x32_bf16 v[12:15], v[134:137], v[184:187], v[12:15]
	v_mfma_f32_16x16x32_bf16 v[8:11], v[152:155], v[184:187], v[8:11]
	v_mfma_f32_16x16x32_bf16 v[60:63], v[138:141], v[164:167], v[60:63]
	v_mfma_f32_16x16x32_bf16 v[56:59], v[156:159], v[164:167], v[56:59]
	v_mfma_f32_16x16x32_bf16 v[44:47], v[138:141], v[172:175], v[44:47]
	v_mfma_f32_16x16x32_bf16 v[40:43], v[156:159], v[172:175], v[40:43]
	v_mfma_f32_16x16x32_bf16 v[28:31], v[138:141], v[180:183], v[28:31]
	v_mfma_f32_16x16x32_bf16 v[24:27], v[156:159], v[180:183], v[24:27]
	v_mfma_f32_16x16x32_bf16 v[12:15], v[138:141], v[188:191], v[12:15]
	v_mfma_f32_16x16x32_bf16 v[8:11], v[156:159], v[188:191], v[8:11]
	s_barrier
; #define G_STAGE(bufoff, gbase, voff) do { _Pragma("unroll") for (int _i = 0; _i < 2; ++_i) \
;         __builtin_amdgcn_global_load_lds((const unsigned*)((const char*)(gbase) + (voff)[_i]), (LAS unsigned*)(lds + (bufoff) + ldsw + _i * 8192), 16, 0, 0); } while (0)
; #define G_LDA(dst, b, h) do { _Pragma("unroll") for (int m = 0; m < 4; ++m) _Pragma("unroll") for (int k = 0; k < 2; ++k) dst[m][k] = *(const LAS bf16x8*)(lds + G_SA(b, h) + aoff + m * 2048 + k * 1024); } while (0)
; #define G_LDB(dst, b, h) do { _Pragma("unroll") for (int n = 0; n < 2; ++n) _Pragma("unroll") for (int k = 0; k < 2; ++k) dst[n][k] = *(const LAS bf16x8*)(lds + G_SB(b, h) + boff + n * 2048 + k * 1024); } while (0)
; #define G_MMA(ai, bj, At, Bt) do { __builtin_amdgcn_s_setprio(1); _Pragma("unroll") for (int m = 0; m < 4; ++m) _Pragma("unroll") for (int n = 0; n < 2; ++n) _Pragma("unroll") for (int k = 0; k < 2; ++k) \
;         acc[ai][bj][m][n] = __builtin_amdgcn_mfma_f32_16x16x32_bf16(Bt[n][k], At[m][k], acc[ai][bj][m][n], 0, 0, 0); __builtin_amdgcn_s_setprio(0); } while (0)
; #define G_WAIT_V(n) asm volatile("s_waitcnt vmcnt(" #n ")" ::: "memory")
; #define G_WAIT_L(n) asm volatile("s_waitcnt lgkmcnt(" #n ")" ::: "memory")
; #define G_BAR __builtin_amdgcn_s_barrier()
; #define G_SCHED __builtin_amdgcn_sched_barrier(0)
; template <class J>
; DI void gemm_phase(LAS unsigned char* lds, const J& job) {
;     ...
;       G_STAGE(G_SB(0, 1), b2 + hstepB, voffB);
;       G_WAIT_V(6); G_BAR; G_MMA(1, 1, At, B1); G_BAR;
;       G_LDB(B0, 1, 0); G_SCHED; G_LDA(At, 1, 0); G_STAGE(G_SA(0, 1), a2 + hstepA, voffA);
;       G_WAIT_L(8); G_BAR; G_WAIT_L(0); G_MMA(0, 0, At, B0); G_BAR; G_SCHED;
;       G_LDB(B1, 1, 1); G_STAGE(G_SB(1, 0), b3, voffB);
;       G_BAR; G_WAIT_L(0); G_MMA(0, 1, At, B1); G_BAR;
;       G_LDA(At, 1, 1); G_STAGE(G_SA(1, 0), a3, voffA);
	s_add_u32 s10, s76, 0x80000
	s_addc_u32 s11, s77, 0
	s_add_i32 s0, s0, s5
	v_lshl_add_u64 v[134:135], s[10:11], 0, v[146:147]
	s_mov_b32 m0, s0
	s_nop 0
	global_load_lds_dwordx4 v[134:135], off
	v_lshl_add_u64 v[134:135], s[10:11], 0, v[132:133]
	s_add_i32 m0, s0, 0x2000
	s_nop 0
	global_load_lds_dwordx4 v[134:135], off
	s_waitcnt vmcnt(6)
	s_barrier
	v_mfma_f32_16x16x32_bf16 v[52:55], v[192:195], v[160:163], v[52:55]
	v_mfma_f32_16x16x32_bf16 v[48:51], v[200:203], v[160:163], v[48:51]
	v_mfma_f32_16x16x32_bf16 v[36:39], v[192:195], v[168:171], v[36:39]
	v_mfma_f32_16x16x32_bf16 v[32:35], v[200:203], v[168:171], v[32:35]
	v_mfma_f32_16x16x32_bf16 v[20:23], v[192:195], v[176:179], v[20:23]
	v_mfma_f32_16x16x32_bf16 v[16:19], v[200:203], v[176:179], v[16:19]
	v_mfma_f32_16x16x32_bf16 v[4:7], v[192:195], v[184:187], v[4:7]
	v_mfma_f32_16x16x32_bf16 v[0:3], v[200:203], v[184:187], v[0:3]
	v_mfma_f32_16x16x32_bf16 v[52:55], v[196:199], v[164:167], v[52:55]
	v_mfma_f32_16x16x32_bf16 v[48:51], v[204:207], v[164:167], v[48:51]
	v_mfma_f32_16x16x32_bf16 v[36:39], v[196:199], v[172:175], v[36:39]
	v_mfma_f32_16x16x32_bf16 v[32:35], v[204:207], v[172:175], v[32:35]
	v_mfma_f32_16x16x32_bf16 v[20:23], v[196:199], v[180:183], v[20:23]
	v_mfma_f32_16x16x32_bf16 v[16:19], v[204:207], v[180:183], v[16:19]
	v_mfma_f32_16x16x32_bf16 v[4:7], v[196:199], v[188:191], v[4:7]
	v_mfma_f32_16x16x32_bf16 v[0:3], v[204:207], v[188:191], v[0:3]
	s_barrier
	s_add_i32 s0, s88, 0x100
	v_add_u32_e32 v142, s0, v150
	ds_read_b128 v[134:137], v142
	ds_read_b128 v[138:141], v142 offset:1024
	ds_read_b128 v[152:155], v142 offset:2048
	ds_read_b128 v[156:159], v142 offset:3072
	s_add_u32 s10, s74, 0x80000
	s_addc_u32 s11, s75, 0
	s_mov_b32 m0, s25
	v_lshl_add_u64 v[142:143], s[10:11], 0, v[128:129]
	ds_read_b128 v[160:163], v151 offset:32768
	ds_read_b128 v[164:167], v151 offset:33792
	ds_read_b128 v[168:171], v151 offset:34816
	ds_read_b128 v[172:175], v151 offset:35840
	ds_read_b128 v[176:179], v151 offset:36864
	ds_read_b128 v[180:183], v151 offset:37888
	ds_read_b128 v[184:187], v151 offset:38912
	ds_read_b128 v[188:191], v151 offset:39936
	global_load_lds_dwordx4 v[142:143], off
	v_lshl_add_u64 v[142:143], s[10:11], 0, v[130:131]
	s_mov_b32 m0, s36
	s_nop 0
	global_load_lds_dwordx4 v[142:143], off
	s_waitcnt lgkmcnt(8)
	s_barrier
	s_waitcnt lgkmcnt(0)
	v_mfma_f32_16x16x32_bf16 v[124:127], v[134:137], v[160:163], v[124:127]
	v_mfma_f32_16x16x32_bf16 v[120:123], v[152:155], v[160:163], v[120:123]
	v_mfma_f32_16x16x32_bf16 v[108:111], v[134:137], v[168:171], v[108:111]
	v_mfma_f32_16x16x32_bf16 v[104:107], v[152:155], v[168:171], v[104:107]
	v_mfma_f32_16x16x32_bf16 v[92:95], v[134:137], v[176:179], v[92:95]
	v_mfma_f32_16x16x32_bf16 v[88:91], v[152:155], v[176:179], v[88:91]
	v_mfma_f32_16x16x32_bf16 v[76:79], v[134:137], v[184:187], v[76:79]
	v_mfma_f32_16x16x32_bf16 v[72:75], v[152:155], v[184:187], v[72:75]
	v_mfma_f32_16x16x32_bf16 v[124:127], v[138:141], v[164:167], v[124:127]
	v_mfma_f32_16x16x32_bf16 v[120:123], v[156:159], v[164:167], v[120:123]
	v_mfma_f32_16x16x32_bf16 v[108:111], v[138:141], v[172:175], v[108:111]
	v_mfma_f32_16x16x32_bf16 v[104:107], v[156:159], v[172:175], v[104:107]
	v_mfma_f32_16x16x32_bf16 v[92:95], v[138:141], v[180:183], v[92:95]
	v_mfma_f32_16x16x32_bf16 v[88:91], v[156:159], v[180:183], v[88:91]
	v_mfma_f32_16x16x32_bf16 v[76:79], v[138:141], v[188:191], v[76:79]
	v_mfma_f32_16x16x32_bf16 v[72:75], v[156:159], v[188:191], v[72:75]
	s_barrier
	s_add_i32 s1, s89, 0x100
	v_add_u32_e32 v142, s1, v150
	s_add_i32 s0, s0, s5
	ds_read_b128 v[192:195], v142
	ds_read_b128 v[196:199], v142 offset:1024
	ds_read_b128 v[200:203], v142 offset:2048
	ds_read_b128 v[204:207], v142 offset:3072
	v_lshl_add_u64 v[142:143], s[70:71], 0, v[146:147]
	s_mov_b32 m0, s0
	s_nop 0
	global_load_lds_dwordx4 v[142:143], off
	v_lshl_add_u64 v[142:143], s[70:71], 0, v[132:133]
	s_add_i32 m0, s0, 0x2000
	s_nop 0
	global_load_lds_dwordx4 v[142:143], off
	s_barrier
	s_waitcnt lgkmcnt(0)
	v_mfma_f32_16x16x32_bf16 v[116:119], v[192:195], v[160:163], v[116:119]
	v_mfma_f32_16x16x32_bf16 v[112:115], v[200:203], v[160:163], v[112:115]
	v_mfma_f32_16x16x32_bf16 v[100:103], v[192:195], v[168:171], v[100:103]
	v_mfma_f32_16x16x32_bf16 v[96:99], v[200:203], v[168:171], v[96:99]
	v_mfma_f32_16x16x32_bf16 v[84:87], v[192:195], v[176:179], v[84:87]
	v_mfma_f32_16x16x32_bf16 v[80:83], v[200:203], v[176:179], v[80:83]
	v_mfma_f32_16x16x32_bf16 v[68:71], v[192:195], v[184:187], v[68:71]
	v_mfma_f32_16x16x32_bf16 v[64:67], v[200:203], v[184:187], v[64:67]
	v_mfma_f32_16x16x32_bf16 v[116:119], v[196:199], v[164:167], v[116:119]
	v_mfma_f32_16x16x32_bf16 v[112:115], v[204:207], v[164:167], v[112:115]
	v_mfma_f32_16x16x32_bf16 v[100:103], v[196:199], v[172:175], v[100:103]
	v_mfma_f32_16x16x32_bf16 v[96:99], v[204:207], v[172:175], v[96:99]
	v_mfma_f32_16x16x32_bf16 v[84:87], v[196:199], v[180:183], v[84:87]
	v_mfma_f32_16x16x32_bf16 v[80:83], v[204:207], v[180:183], v[80:83]
	v_mfma_f32_16x16x32_bf16 v[68:71], v[196:199], v[188:191], v[68:71]
	v_mfma_f32_16x16x32_bf16 v[64:67], v[204:207], v[188:191], v[64:67]
	s_barrier
; DI unsigned pk2(float lo, float hi) { unsigned r; asm("v_cvt_pk_bf16_f32 %0, %1, %2" : "=v"(r) : "v"(lo), "v"(hi)); return r; }
; #define G_STAGE(bufoff, gbase, voff) do { _Pragma("unroll") for (int _i = 0; _i < 2; ++_i) \
;         __builtin_amdgcn_global_load_lds((const unsigned*)((const char*)(gbase) + (voff)[_i]), (LAS unsigned*)(lds + (bufoff) + ldsw + _i * 8192), 16, 0, 0); } while (0)
; #define G_LDA(dst, b, h) do { _Pragma("unroll") for (int m = 0; m < 4; ++m) _Pragma("unroll") for (int k = 0; k < 2; ++k) dst[m][k] = *(const LAS bf16x8*)(lds + G_SA(b, h) + aoff + m * 2048 + k * 1024); } while (0)
; #define G_MMA(ai, bj, At, Bt) do { __builtin_amdgcn_s_setprio(1); _Pragma("unroll") for (int m = 0; m < 4; ++m) _Pragma("unroll") for (int n = 0; n < 2; ++n) _Pragma("unroll") for (int k = 0; k < 2; ++k) \
;         acc[ai][bj][m][n] = __builtin_amdgcn_mfma_f32_16x16x32_bf16(Bt[n][k], At[m][k], acc[ai][bj][m][n], 0, 0, 0); __builtin_amdgcn_s_setprio(0); } while (0)
; #define G_WAIT_V(n) asm volatile("s_waitcnt vmcnt(" #n ")" ::: "memory")
; #define G_WAIT_L(n) asm volatile("s_waitcnt lgkmcnt(" #n ")" ::: "memory")
; #define G_BAR __builtin_amdgcn_s_barrier()
; #define G_SCHED __builtin_amdgcn_sched_barrier(0)
; template <class J>
; DI void gemm_phase(LAS unsigned char* lds, const J& job) {
;     ...
;       G_LDA(At, 1, 1); G_STAGE(G_SA(1, 0), a3, voffA);
;       G_BAR; G_WAIT_L(0); G_MMA(1, 0, At, B0); G_BAR; G_SCHED;
;       G_STAGE(G_SB(1, 1), b3 + hstepB, voffB);
;       G_WAIT_V(6); G_BAR; G_MMA(1, 1, At, B1); G_BAR;
;   DI void epi(const Acc& acc, const Unit& u, int wr, int wc, int fr, int fq) const {
;     ...
;           const int col = u.pn * 256 + bj * HALF + wc * 32 + 8 * fq;
;           const f32x4 v0 = acc[ai][bj][m][0], v1 = acc[ai][bj][m][1];
;           const int row = u.pm * 256 + rl;
;           u32x4 o; o.x = pk2(v0.x, v0.y); o.y = pk2(v0.z, v0.w); o.z = pk2(v1.x, v1.y); o.w = pk2(v1.z, v1.w);
;           *(u32x4*)(proj + (size_t)row * NPROJ + col) = o;
;           if (u.pn >= 8 && u.pn < 12) {
;             const int isv = u.pn >= 10; const int cc = col - (isv ? C_BV : C_BK);
;             float* dst = out + (isv ? O_VP : O_KP) + ((size_t)l * TP + row) * 512 + cc;
;             *(f32x4*)dst = v0; *(f32x4*)(dst + 4) = v1;
	s_mov_b32 m0, s45
	v_lshl_add_u64 v[142:143], s[72:73], 0, v[128:129]
	ds_read_b128 v[160:163], v151 offset:49152
	ds_read_b128 v[164:167], v151 offset:50176
	ds_read_b128 v[168:171], v151 offset:51200
	ds_read_b128 v[172:175], v151 offset:52224
	ds_read_b128 v[176:179], v151 offset:53248
	ds_read_b128 v[180:183], v151 offset:54272
	ds_read_b128 v[184:187], v151 offset:55296
	ds_read_b128 v[188:191], v151 offset:56320
	global_load_lds_dwordx4 v[142:143], off
	v_lshl_add_u64 v[142:143], s[72:73], 0, v[130:131]
	s_mov_b32 m0, s65
	s_nop 0
	global_load_lds_dwordx4 v[142:143], off
	s_barrier
	s_waitcnt lgkmcnt(0)
	v_mfma_f32_16x16x32_bf16 v[60:63], v[134:137], v[160:163], v[60:63]
	v_mfma_f32_16x16x32_bf16 v[56:59], v[152:155], v[160:163], v[56:59]
	v_mfma_f32_16x16x32_bf16 v[44:47], v[134:137], v[168:171], v[44:47]
	v_mfma_f32_16x16x32_bf16 v[40:43], v[152:155], v[168:171], v[40:43]
	v_mfma_f32_16x16x32_bf16 v[28:31], v[134:137], v[176:179], v[28:31]
	v_mfma_f32_16x16x32_bf16 v[24:27], v[152:155], v[176:179], v[24:27]
	v_mfma_f32_16x16x32_bf16 v[12:15], v[134:137], v[184:187], v[12:15]
	v_mfma_f32_16x16x32_bf16 v[8:11], v[152:155], v[184:187], v[8:11]
	v_mfma_f32_16x16x32_bf16 v[60:63], v[138:141], v[164:167], v[60:63]
	v_mfma_f32_16x16x32_bf16 v[56:59], v[156:159], v[164:167], v[56:59]
	v_mfma_f32_16x16x32_bf16 v[44:47], v[138:141], v[172:175], v[44:47]
	v_mfma_f32_16x16x32_bf16 v[40:43], v[156:159], v[172:175], v[40:43]
	v_mfma_f32_16x16x32_bf16 v[28:31], v[138:141], v[180:183], v[28:31]
	v_mfma_f32_16x16x32_bf16 v[24:27], v[156:159], v[180:183], v[24:27]
	v_mfma_f32_16x16x32_bf16 v[12:15], v[138:141], v[188:191], v[12:15]
	v_mfma_f32_16x16x32_bf16 v[8:11], v[156:159], v[188:191], v[8:11]
	s_barrier
	s_add_u32 s10, s70, 0x80000
	s_addc_u32 s11, s71, 0
	s_add_i32 s0, s1, s5
	v_lshl_add_u64 v[134:135], s[10:11], 0, v[146:147]
	s_mov_b32 m0, s0
	s_nop 0
	global_load_lds_dwordx4 v[134:135], off
	v_lshl_add_u64 v[134:135], s[10:11], 0, v[132:133]
	s_add_i32 m0, s0, 0x2000
	s_nop 0
	global_load_lds_dwordx4 v[134:135], off
	s_waitcnt vmcnt(6)
	s_barrier
	v_mfma_f32_16x16x32_bf16 v[52:55], v[192:195], v[160:163], v[52:55]
	v_mfma_f32_16x16x32_bf16 v[48:51], v[200:203], v[160:163], v[48:51]
	v_mfma_f32_16x16x32_bf16 v[36:39], v[192:195], v[168:171], v[36:39]
	v_mfma_f32_16x16x32_bf16 v[32:35], v[200:203], v[168:171], v[32:35]
	v_mfma_f32_16x16x32_bf16 v[20:23], v[192:195], v[176:179], v[20:23]
	v_mfma_f32_16x16x32_bf16 v[16:19], v[200:203], v[176:179], v[16:19]
	v_mfma_f32_16x16x32_bf16 v[4:7], v[192:195], v[184:187], v[4:7]
	v_mfma_f32_16x16x32_bf16 v[0:3], v[200:203], v[184:187], v[0:3]
	v_mfma_f32_16x16x32_bf16 v[52:55], v[196:199], v[164:167], v[52:55]
	v_mfma_f32_16x16x32_bf16 v[48:51], v[204:207], v[164:167], v[48:51]
	v_mfma_f32_16x16x32_bf16 v[36:39], v[196:199], v[172:175], v[36:39]
	v_mfma_f32_16x16x32_bf16 v[32:35], v[204:207], v[172:175], v[32:35]
	v_mfma_f32_16x16x32_bf16 v[20:23], v[196:199], v[180:183], v[20:23]
	v_mfma_f32_16x16x32_bf16 v[16:19], v[204:207], v[180:183], v[16:19]
	v_mfma_f32_16x16x32_bf16 v[4:7], v[196:199], v[188:191], v[4:7]
	v_mfma_f32_16x16x32_bf16 v[0:3], v[204:207], v[188:191], v[0:3]
	s_add_i32 s6, s6, 2
	s_addk_i32 s56, 0x100
	s_addk_i32 s7, 0x100
	s_cmp_gt_u32 s6, 29
	s_barrier
	s_cbranch_scc0 .LBB0_282
	v_mov_b32_e32 v135, v148
	v_mov_b32_e32 v134, v149
	s_lshl_b32 s0, s64, 8
	s_or_b32 s0, s0, s38
	v_lshl_add_u32 v134, v134, 3, s0
	s_lshl_b32 s0, s8, 8
	s_add_i32 s0, s0, s37
	v_add_u32_e32 v136, s0, v135
	s_and_b32 s0, s64, -4
	s_cmp_eq_u32 s0, 8
	s_cselect_b64 s[66:67], -1, 0
	s_cmp_gt_u32 s64, 9
	s_cselect_b64 s[6:7], -1, 0
	s_and_b64 s[6:7], s[6:7], exec
	s_movk_i32 s1, 0xf600
	v_mov_b64_e32 v[138:139], s[26:27]
	s_cselect_b32 s7, s1, 0xfffff800
	s_mov_b32 s1, 0x3040000
	v_ashrrev_i32_e32 v137, 31, v136
	v_mad_i64_i32 v[138:139], s[8:9], v136, s92, v[138:139]
	v_ashrrev_i32_e32 v135, 31, v134
	s_cselect_b32 s6, s1, 0x2040000
	s_cmp_lg_u32 s0, 8
	v_lshlrev_b64 v[140:141], 11, v[136:137]
	v_lshl_add_u64 v[142:143], v[134:135], 1, v[138:139]
	v_add_u32_e32 v138, s7, v134
	v_cvt_pk_bf16_f32 v152, v124, v125
	v_cvt_pk_bf16_f32 v153, v126, v127
	v_cvt_pk_bf16_f32 v154, v120, v121
	v_cvt_pk_bf16_f32 v155, v122, v123
	global_store_dwordx4 v[142:143], v[152:155], off
	s_cbranch_scc1 .LBB0_285
	s_lshl_b32 s0, s6, 2
	s_add_u32 s8, s83, s0
	s_addc_u32 s9, s86, 0
	v_lshl_add_u64 v[152:153], s[8:9], 0, v[140:141]
	v_ashrrev_i32_e32 v139, 31, v138
	v_lshl_add_u64 v[152:153], v[138:139], 2, v[152:153]
	global_store_dwordx4 v[152:153], v[124:127], off
	global_store_dwordx4 v[152:153], v[120:123], off offset:16
